# v16 plus removal of 90 canonicalising v_max x,x in attention softmax (bit-exact)
# speedup vs baseline: 1.0032x; 1.0032x over previous
.LBB0_855:
	s_and_b64 s[10:11], s[4:5], s[10:11]
	s_andn2_b64 vcc, exec, s[10:11]
	s_cbranch_vccnz .LBB0_861
	v_max_f32_e32 v0, v96, v97
	v_max3_f32 v0, v0, v98, v99
	v_max3_f32 v0, v0, v100, v101
	v_max3_f32 v0, v0, v102, v103
	v_max3_f32 v0, v0, v104, v105
	v_max3_f32 v0, v0, v106, v107
	v_max3_f32 v0, v0, v108, v109
	v_max3_f32 v0, v0, v110, v111
	v_max3_f32 v0, v0, v80, v81
	v_max3_f32 v0, v0, v82, v83
	v_max3_f32 v0, v0, v84, v85
	v_max3_f32 v0, v0, v86, v87
	v_max3_f32 v0, v0, v88, v89
	v_max3_f32 v0, v0, v90, v91
	v_max3_f32 v0, v0, v92, v93
	v_max3_f32 v0, v0, v94, v95
	v_mov_b32_e32 v2, v0
	s_nop 1
	v_permlane32_swap_b32_e32 v0, v2
	v_max_f32_e32 v0, v0, v2
	v_sub_f32_e32 v2, v0, v156
	v_cmp_ge_f32_e32 vcc, s86, v2
	s_cmp_eq_u64 vcc, exec
	v_max_f32_e32 v2, v156, v0
	s_cselect_b64 vcc, -1, 0
	v_sub_f32_e32 v0, v156, v2
	v_cndmask_b32_e32 v156, v2, v156, vcc
	v_sub_f32_e32 v14, v87, v156
	v_exp_f32_e32 v87, v14
	v_sub_f32_e32 v14, v104, v156
	v_sub_f32_e32 v2, v96, v156
	v_exp_f32_e32 v96, v14
	v_sub_f32_e32 v14, v88, v156
	v_exp_f32_e32 v88, v14
	v_sub_f32_e32 v14, v105, v156
	v_sub_f32_e32 v4, v97, v156
	v_exp_f32_e32 v97, v14
	v_sub_f32_e32 v14, v89, v156
	v_exp_f32_e32 v89, v14
	v_sub_f32_e32 v14, v106, v156
	v_sub_f32_e32 v6, v98, v156
	v_exp_f32_e32 v98, v14
	v_sub_f32_e32 v14, v90, v156
	v_exp_f32_e32 v90, v14
	v_sub_f32_e32 v14, v107, v156
	v_sub_f32_e32 v8, v99, v156
	v_exp_f32_e32 v99, v14
	v_sub_f32_e32 v14, v91, v156
	v_exp_f32_e32 v91, v14
	v_sub_f32_e32 v14, v108, v156
	v_sub_f32_e32 v10, v100, v156
	v_exp_f32_e32 v100, v14
	v_sub_f32_e32 v14, v92, v156
	v_sub_f32_e32 v11, v84, v156
	v_exp_f32_e32 v92, v14
	v_sub_f32_e32 v14, v109, v156
	v_sub_f32_e32 v3, v80, v156
	v_exp_f32_e32 v84, v11
	v_sub_f32_e32 v11, v101, v156
	v_exp_f32_e32 v101, v14
	v_sub_f32_e32 v14, v93, v156
	v_exp_f32_e32 v2, v2
	v_exp_f32_e32 v3, v3
	v_sub_f32_e32 v5, v81, v156
	v_sub_f32_e32 v12, v85, v156
	v_exp_f32_e32 v93, v14
	v_sub_f32_e32 v14, v110, v156
	v_exp_f32_e32 v4, v4
	v_exp_f32_e32 v5, v5
	v_sub_f32_e32 v7, v82, v156
	v_exp_f32_e32 v85, v12
	v_sub_f32_e32 v12, v102, v156
	v_exp_f32_e32 v102, v14
	v_sub_f32_e32 v14, v94, v156
	v_exp_f32_e32 v6, v6
	v_exp_f32_e32 v7, v7
	v_sub_f32_e32 v9, v83, v156
	v_sub_f32_e32 v13, v86, v156
	v_exp_f32_e32 v94, v14
	v_sub_f32_e32 v14, v111, v156
	v_exp_f32_e32 v8, v8
	v_exp_f32_e32 v9, v9
	v_exp_f32_e32 v86, v13
	v_sub_f32_e32 v13, v103, v156
	v_exp_f32_e32 v103, v14
	v_sub_f32_e32 v14, v95, v156
	v_exp_f32_e32 v10, v10
	v_exp_f32_e32 v95, v14
	v_add_f32_e32 v14, v2, v3
	v_exp_f32_e32 v11, v11
	v_add_f32_e32 v14, 0, v14
	v_add_f32_e32 v15, v4, v5
	v_exp_f32_e32 v12, v12
	v_add_f32_e32 v14, v15, v14
	v_add_f32_e32 v15, v6, v7
	v_exp_f32_e32 v13, v13
	v_add_f32_e32 v14, v15, v14
	v_add_f32_e32 v15, v8, v9
	v_add_f32_e32 v14, v15, v14
	v_add_f32_e32 v15, v10, v84
	v_add_f32_e32 v14, v15, v14
	v_add_f32_e32 v15, v11, v85
	v_add_f32_e32 v14, v15, v14
	v_add_f32_e32 v15, v12, v86
	v_add_f32_e32 v14, v15, v14
	v_add_f32_e32 v15, v13, v87
	v_add_f32_e32 v14, v15, v14
	v_add_f32_e32 v15, v96, v88
	v_add_f32_e32 v14, v15, v14
	v_add_f32_e32 v15, v97, v89
	v_add_f32_e32 v14, v15, v14
	v_add_f32_e32 v15, v98, v90
	v_add_f32_e32 v14, v15, v14
	v_add_f32_e32 v15, v99, v91
	v_add_f32_e32 v14, v15, v14
	v_add_f32_e32 v15, v100, v92
	v_add_f32_e32 v14, v15, v14
	v_add_f32_e32 v15, v101, v93
	v_add_f32_e32 v14, v15, v14
	v_add_f32_e32 v15, v102, v94
	v_exp_f32_e32 v0, v0
	v_add_f32_e32 v14, v15, v14
	v_add_f32_e32 v15, v103, v95
	v_add_f32_e32 v14, v15, v14
	v_mov_b32_e32 v15, v14
	v_cvt_pk_bf16_f32 v80, v2, v4
	v_cvt_pk_bf16_f32 v81, v6, v8
	v_cvt_pk_bf16_f32 v82, v10, v11
	v_cvt_pk_bf16_f32 v83, v12, v13
	v_cvt_pk_bf16_f32 v10, v96, v97
	v_cvt_pk_bf16_f32 v11, v98, v99
	v_cvt_pk_bf16_f32 v12, v100, v101
	v_cvt_pk_bf16_f32 v13, v102, v103
	v_cvt_pk_bf16_f32 v6, v3, v5
	v_cvt_pk_bf16_f32 v7, v7, v9
	v_cvt_pk_bf16_f32 v8, v84, v85
	v_cvt_pk_bf16_f32 v9, v86, v87
	v_cvt_pk_bf16_f32 v2, v88, v89
	v_cvt_pk_bf16_f32 v3, v90, v91
	v_cvt_pk_bf16_f32 v4, v92, v93
	v_cvt_pk_bf16_f32 v5, v94, v95
	s_nop 1
	v_permlane32_swap_b32_e32 v14, v15
	v_permlane32_swap_b32_e32 v80, v82
	v_permlane32_swap_b32_e32 v81, v83
	v_permlane32_swap_b32_e32 v10, v12
	v_permlane32_swap_b32_e32 v11, v13
	v_permlane32_swap_b32_e32 v6, v8
	v_permlane32_swap_b32_e32 v7, v9
	v_permlane32_swap_b32_e32 v2, v4
	v_permlane32_swap_b32_e32 v3, v5
	s_cbranch_vccnz .LBB0_860
	s_and_saveexec_b64 s[10:11], s[0:1]
	ds_write_b32 v152, v0 offset:128
	s_or_b64 exec, exec, s[10:11]
	s_waitcnt lgkmcnt(0)
	v_add_u32_e32 v96, v150, v151
	ds_read_b128 v[84:87], v96 offset:224
	ds_read_b128 v[88:91], v96 offset:192
	ds_read_b128 v[92:95], v96 offset:160
	ds_read_b128 v[96:99], v96 offset:128
	s_waitcnt lgkmcnt(0)
	v_pk_mul_f32 v[76:77], v[76:77], v[84:85]
	v_pk_mul_f32 v[72:73], v[72:73], v[88:89]
	v_pk_mul_f32 v[68:69], v[68:69], v[92:93]
	v_pk_mul_f32 v[78:79], v[78:79], v[86:87]
	v_pk_mul_f32 v[74:75], v[74:75], v[90:91]
	v_pk_mul_f32 v[70:71], v[70:71], v[94:95]
	v_pk_mul_f32 v[66:67], v[66:67], v[98:99]
	v_pk_mul_f32 v[64:65], v[64:65], v[96:97]
	v_pk_mul_f32 v[60:61], v[60:61], v[84:85]
	v_pk_mul_f32 v[56:57], v[56:57], v[88:89]
	v_pk_mul_f32 v[52:53], v[52:53], v[92:93]
	v_pk_mul_f32 v[62:63], v[62:63], v[86:87]
	v_pk_mul_f32 v[58:59], v[58:59], v[90:91]
	v_pk_mul_f32 v[54:55], v[54:55], v[94:95]
	v_pk_mul_f32 v[50:51], v[50:51], v[98:99]
	v_pk_mul_f32 v[48:49], v[48:49], v[96:97]
	v_pk_mul_f32 v[44:45], v[44:45], v[84:85]
	v_pk_mul_f32 v[40:41], v[40:41], v[88:89]
	v_pk_mul_f32 v[36:37], v[36:37], v[92:93]
	v_pk_mul_f32 v[46:47], v[46:47], v[86:87]
	v_pk_mul_f32 v[42:43], v[42:43], v[90:91]
	v_pk_mul_f32 v[38:39], v[38:39], v[94:95]
	v_pk_mul_f32 v[34:35], v[34:35], v[98:99]
	v_pk_mul_f32 v[32:33], v[32:33], v[96:97]
	v_pk_mul_f32 v[28:29], v[28:29], v[84:85]
	v_pk_mul_f32 v[24:25], v[24:25], v[88:89]
	v_pk_mul_f32 v[20:21], v[20:21], v[92:93]
	v_pk_mul_f32 v[30:31], v[30:31], v[86:87]
	v_pk_mul_f32 v[26:27], v[26:27], v[90:91]
	v_pk_mul_f32 v[22:23], v[22:23], v[94:95]
	v_pk_mul_f32 v[18:19], v[18:19], v[98:99]
	v_pk_mul_f32 v[16:17], v[16:17], v[96:97]

.LBB0_861:
	s_lshl_b32 s10, s16, 14
	s_add_i32 s10, s10, 0
	s_add_i32 s10, s10, 0x10000
	v_add3_u32 v0, s10, v155, v154
	v_add3_u32 v6, s10, v157, v154
	v_add3_u32 v7, s10, v158, v154
	v_add3_u32 v8, s10, v159, v154
	ds_read_b128 v[216:219], v0
	ds_read_b128 v[220:223], v0 offset:8192
	ds_read_b128 v[224:227], v6
	ds_read_b128 v[228:231], v6 offset:8192
	ds_read_b128 v[232:235], v7
	ds_read_b128 v[236:239], v7 offset:8192
	ds_read_b128 v[240:243], v8
	ds_read_b128 v[244:247], v8 offset:8192
	s_waitcnt lgkmcnt(6)
	v_mfma_f32_32x32x16_bf16 v[96:111], v[216:219], v[112:115], 0
	v_mfma_f32_32x32x16_bf16 v[80:95], v[220:223], v[112:115], 0
	ds_read_b128 v[216:219], v0 offset:128
	ds_read_b128 v[220:223], v0 offset:8320
	s_waitcnt lgkmcnt(6)
	v_mfma_f32_32x32x16_bf16 v[96:111], v[224:227], v[116:119], v[96:111]
	v_mfma_f32_32x32x16_bf16 v[80:95], v[228:231], v[116:119], v[80:95]
	ds_read_b128 v[224:227], v6 offset:128
	ds_read_b128 v[228:231], v6 offset:8320
	s_waitcnt lgkmcnt(6)
	v_mfma_f32_32x32x16_bf16 v[96:111], v[232:235], v[120:123], v[96:111]
	v_mfma_f32_32x32x16_bf16 v[80:95], v[236:239], v[120:123], v[80:95]
	ds_read_b128 v[232:235], v7 offset:128
	ds_read_b128 v[236:239], v7 offset:8320
	s_waitcnt lgkmcnt(6)
	v_mfma_f32_32x32x16_bf16 v[96:111], v[240:243], v[124:127], v[96:111]
	v_mfma_f32_32x32x16_bf16 v[80:95], v[244:247], v[124:127], v[80:95]
	ds_read_b128 v[240:243], v8 offset:128
	ds_read_b128 v[244:247], v8 offset:8320
	s_andn2_b64 vcc, exec, s[6:7]
	s_waitcnt lgkmcnt(6)
	v_mfma_f32_32x32x16_bf16 v[96:111], v[216:219], v[128:131], v[96:111]
	v_mfma_f32_32x32x16_bf16 v[80:95], v[220:223], v[128:131], v[80:95]
	s_waitcnt lgkmcnt(4)
	v_mfma_f32_32x32x16_bf16 v[96:111], v[224:227], v[132:135], v[96:111]
	v_mfma_f32_32x32x16_bf16 v[80:95], v[228:231], v[132:135], v[80:95]
	s_waitcnt lgkmcnt(2)
	v_mfma_f32_32x32x16_bf16 v[96:111], v[232:235], v[136:139], v[96:111]
	v_mfma_f32_32x32x16_bf16 v[80:95], v[236:239], v[136:139], v[80:95]
	s_waitcnt lgkmcnt(0)
	v_mfma_f32_32x32x16_bf16 v[96:111], v[240:243], v[140:143], v[96:111]
	v_mfma_f32_32x32x16_bf16 v[80:95], v[244:247], v[140:143], v[80:95]
	s_nop 1
	s_cbranch_vccnz .LBB0_871
	s_nop 7
	v_max_f32_e32 v0, v96, v97
	v_max3_f32 v0, v0, v98, v99
	v_max3_f32 v0, v0, v100, v101
	v_max3_f32 v0, v0, v102, v103
	v_max3_f32 v0, v0, v104, v105
	v_max3_f32 v0, v0, v106, v107
	v_max3_f32 v0, v0, v108, v109
	v_max3_f32 v0, v0, v110, v111
	v_max3_f32 v0, v0, v80, v81
	v_max3_f32 v0, v0, v82, v83
	v_max3_f32 v0, v0, v84, v85
	v_max3_f32 v0, v0, v86, v87
	v_max3_f32 v0, v0, v88, v89
	v_max3_f32 v0, v0, v90, v91
	v_max3_f32 v0, v0, v92, v93
	v_max3_f32 v0, v0, v94, v95
	v_mov_b32_e32 v2, v0
	s_nop 1
	v_permlane32_swap_b32_e32 v0, v2
	v_max_f32_e32 v0, v0, v2
	v_sub_f32_e32 v2, v0, v156
	v_cmp_ge_f32_e32 vcc, s86, v2
	s_cmp_eq_u64 vcc, exec
	v_max_f32_e32 v2, v156, v0
	s_cselect_b64 vcc, -1, 0
	v_sub_f32_e32 v0, v156, v2
	v_cndmask_b32_e32 v156, v2, v156, vcc
	v_sub_f32_e32 v2, v96, v156
	v_exp_f32_e32 v96, v2
	v_sub_f32_e32 v2, v80, v156
	v_exp_f32_e32 v80, v2
	v_sub_f32_e32 v2, v97, v156
	v_exp_f32_e32 v97, v2
	v_sub_f32_e32 v2, v81, v156
	v_exp_f32_e32 v81, v2
	v_sub_f32_e32 v2, v98, v156
	v_exp_f32_e32 v98, v2
	v_sub_f32_e32 v2, v82, v156
	v_exp_f32_e32 v82, v2
	v_sub_f32_e32 v2, v99, v156
	v_exp_f32_e32 v99, v2
	v_sub_f32_e32 v2, v83, v156
	v_exp_f32_e32 v83, v2
	v_sub_f32_e32 v2, v100, v156
	v_exp_f32_e32 v100, v2
	v_sub_f32_e32 v2, v84, v156
	v_exp_f32_e32 v84, v2
	v_sub_f32_e32 v2, v101, v156
	v_exp_f32_e32 v101, v2
	v_sub_f32_e32 v2, v85, v156
	v_exp_f32_e32 v85, v2
	v_sub_f32_e32 v2, v102, v156
	v_exp_f32_e32 v102, v2
	v_sub_f32_e32 v2, v86, v156
	v_exp_f32_e32 v86, v2
	v_sub_f32_e32 v2, v103, v156
	v_exp_f32_e32 v103, v2
	v_sub_f32_e32 v2, v87, v156
	v_exp_f32_e32 v87, v2
	v_sub_f32_e32 v2, v104, v156
	v_exp_f32_e32 v104, v2
	v_sub_f32_e32 v2, v88, v156
	v_exp_f32_e32 v88, v2
	v_sub_f32_e32 v2, v105, v156
	v_exp_f32_e32 v105, v2
	v_sub_f32_e32 v2, v89, v156
	v_exp_f32_e32 v89, v2
	v_sub_f32_e32 v2, v106, v156
	v_exp_f32_e32 v106, v2
	v_sub_f32_e32 v2, v90, v156
	v_exp_f32_e32 v90, v2
	v_sub_f32_e32 v2, v107, v156
	v_exp_f32_e32 v107, v2
	v_sub_f32_e32 v2, v91, v156
	v_exp_f32_e32 v91, v2
	v_sub_f32_e32 v2, v108, v156
	v_exp_f32_e32 v108, v2
	v_sub_f32_e32 v2, v92, v156
	v_exp_f32_e32 v92, v2
	v_sub_f32_e32 v2, v109, v156
	v_exp_f32_e32 v109, v2
	v_sub_f32_e32 v2, v93, v156
	v_exp_f32_e32 v93, v2
	v_sub_f32_e32 v2, v110, v156
	v_exp_f32_e32 v110, v2
	v_sub_f32_e32 v2, v94, v156
	v_exp_f32_e32 v94, v2
	v_sub_f32_e32 v2, v111, v156
	v_exp_f32_e32 v111, v2
	v_sub_f32_e32 v2, v95, v156
	v_exp_f32_e32 v95, v2
	v_add_f32_e32 v2, v96, v80
	v_add_f32_e32 v2, 0, v2
	v_add_f32_e32 v3, v97, v81
	v_add_f32_e32 v2, v3, v2
	v_add_f32_e32 v3, v98, v82
	v_add_f32_e32 v2, v3, v2
	v_add_f32_e32 v3, v99, v83
	v_add_f32_e32 v2, v3, v2
	v_add_f32_e32 v3, v100, v84
	v_add_f32_e32 v2, v3, v2
	v_add_f32_e32 v3, v101, v85
	v_add_f32_e32 v2, v3, v2
	v_add_f32_e32 v3, v102, v86
	v_add_f32_e32 v2, v3, v2
	v_add_f32_e32 v3, v103, v87
	v_add_f32_e32 v2, v3, v2
	v_add_f32_e32 v3, v104, v88
	v_add_f32_e32 v2, v3, v2
	v_add_f32_e32 v3, v105, v89
	v_add_f32_e32 v2, v3, v2
	v_add_f32_e32 v3, v106, v90
	v_add_f32_e32 v2, v3, v2
	v_add_f32_e32 v3, v107, v91
	v_add_f32_e32 v2, v3, v2
	v_add_f32_e32 v3, v108, v92
	v_add_f32_e32 v2, v3, v2
	v_add_f32_e32 v3, v109, v93
	v_add_f32_e32 v2, v3, v2
	v_add_f32_e32 v3, v110, v94
	v_exp_f32_e32 v0, v0
	v_add_f32_e32 v2, v3, v2
	v_add_f32_e32 v3, v111, v95
	v_add_f32_e32 v14, v3, v2
	v_mov_b32_e32 v15, v14
	v_cvt_pk_bf16_f32 v144, v96, v97
	v_cvt_pk_bf16_f32 v145, v98, v99
	v_cvt_pk_bf16_f32 v146, v100, v101
	v_cvt_pk_bf16_f32 v147, v102, v103
	v_cvt_pk_bf16_f32 v10, v104, v105
	v_cvt_pk_bf16_f32 v11, v106, v107
	v_cvt_pk_bf16_f32 v12, v108, v109
	v_cvt_pk_bf16_f32 v13, v110, v111
	v_cvt_pk_bf16_f32 v6, v80, v81
	v_cvt_pk_bf16_f32 v7, v82, v83
	v_cvt_pk_bf16_f32 v8, v84, v85
	v_cvt_pk_bf16_f32 v9, v86, v87
	v_cvt_pk_bf16_f32 v2, v88, v89
	v_cvt_pk_bf16_f32 v3, v90, v91
	v_cvt_pk_bf16_f32 v4, v92, v93
	v_cvt_pk_bf16_f32 v5, v94, v95
	s_nop 1
	v_permlane32_swap_b32_e32 v14, v15
	v_permlane32_swap_b32_e32 v144, v146
	v_permlane32_swap_b32_e32 v145, v147
	v_permlane32_swap_b32_e32 v10, v12
	v_permlane32_swap_b32_e32 v11, v13
	v_permlane32_swap_b32_e32 v6, v8
	v_permlane32_swap_b32_e32 v7, v9
	v_permlane32_swap_b32_e32 v2, v4
	v_permlane32_swap_b32_e32 v3, v5
	s_cbranch_vccnz .LBB0_866
	s_and_saveexec_b64 s[10:11], s[0:1]
	ds_write_b32 v152, v0 offset:128
	s_or_b64 exec, exec, s[10:11]
	s_waitcnt lgkmcnt(0)
	v_add_u32_e32 v163, v150, v151
	ds_read_b128 v[164:167], v163 offset:224
	ds_read_b128 v[168:171], v163 offset:192
	ds_read_b128 v[172:175], v163 offset:160
	ds_read_b128 v[180:183], v163 offset:128
	s_waitcnt lgkmcnt(0)
	v_pk_mul_f32 v[76:77], v[76:77], v[164:165]
	v_pk_mul_f32 v[72:73], v[72:73], v[168:169]
	v_pk_mul_f32 v[68:69], v[68:69], v[172:173]
	v_pk_mul_f32 v[78:79], v[78:79], v[166:167]
	v_pk_mul_f32 v[74:75], v[74:75], v[170:171]
	v_pk_mul_f32 v[70:71], v[70:71], v[174:175]
	v_pk_mul_f32 v[66:67], v[66:67], v[182:183]
	v_pk_mul_f32 v[64:65], v[64:65], v[180:181]
	v_pk_mul_f32 v[60:61], v[60:61], v[164:165]
	v_pk_mul_f32 v[56:57], v[56:57], v[168:169]
	v_pk_mul_f32 v[52:53], v[52:53], v[172:173]
	v_pk_mul_f32 v[62:63], v[62:63], v[166:167]
	v_pk_mul_f32 v[58:59], v[58:59], v[170:171]
	v_pk_mul_f32 v[54:55], v[54:55], v[174:175]
	v_pk_mul_f32 v[50:51], v[50:51], v[182:183]
	v_pk_mul_f32 v[48:49], v[48:49], v[180:181]
	v_pk_mul_f32 v[44:45], v[44:45], v[164:165]
	v_pk_mul_f32 v[40:41], v[40:41], v[168:169]
	v_pk_mul_f32 v[36:37], v[36:37], v[172:173]
	v_pk_mul_f32 v[46:47], v[46:47], v[166:167]
	v_pk_mul_f32 v[42:43], v[42:43], v[170:171]
	v_pk_mul_f32 v[38:39], v[38:39], v[174:175]
	v_pk_mul_f32 v[34:35], v[34:35], v[182:183]
	v_pk_mul_f32 v[32:33], v[32:33], v[180:181]
	v_pk_mul_f32 v[28:29], v[28:29], v[164:165]
	v_pk_mul_f32 v[24:25], v[24:25], v[168:169]
	v_pk_mul_f32 v[20:21], v[20:21], v[172:173]
	v_pk_mul_f32 v[30:31], v[30:31], v[166:167]
	v_pk_mul_f32 v[26:27], v[26:27], v[170:171]
	v_pk_mul_f32 v[22:23], v[22:23], v[174:175]
	v_pk_mul_f32 v[18:19], v[18:19], v[182:183]
	v_pk_mul_f32 v[16:17], v[16:17], v[180:181]

.LBB0_873:
	s_andn2_b64 vcc, exec, s[4:5]
	s_cbranch_vccnz .LBB0_879
	v_max_f32_e32 v0, v96, v97
	v_max3_f32 v0, v0, v98, v99
	v_max3_f32 v0, v0, v100, v101
	v_max3_f32 v0, v0, v102, v103
	v_max3_f32 v0, v0, v104, v105
	v_max3_f32 v0, v0, v106, v107
	v_max3_f32 v0, v0, v108, v109
	v_max3_f32 v0, v0, v110, v111
	v_max3_f32 v0, v0, v80, v81
	v_max3_f32 v0, v0, v82, v83
	v_max3_f32 v0, v0, v84, v85
	v_max3_f32 v0, v0, v86, v87
	v_max3_f32 v0, v0, v88, v89
	v_max3_f32 v0, v0, v90, v91
	v_max3_f32 v0, v0, v92, v93
	v_max3_f32 v0, v0, v94, v95
	v_mov_b32_e32 v2, v0
	s_nop 1
	v_permlane32_swap_b32_e32 v0, v2
	v_max_f32_e32 v0, v0, v2
	v_sub_f32_e32 v2, v0, v156
	v_cmp_ge_f32_e32 vcc, s86, v2
	s_cmp_eq_u64 vcc, exec
	v_max_f32_e32 v2, v156, v0
	s_cselect_b64 vcc, -1, 0
	v_sub_f32_e32 v0, v156, v2
	v_cndmask_b32_e32 v2, v2, v156, vcc
	v_sub_f32_e32 v14, v87, v2
	v_exp_f32_e32 v87, v14
	v_sub_f32_e32 v14, v104, v2
	v_sub_f32_e32 v5, v97, v2
	v_exp_f32_e32 v97, v14
	v_sub_f32_e32 v14, v88, v2
	v_exp_f32_e32 v88, v14
	v_sub_f32_e32 v14, v105, v2
	v_sub_f32_e32 v7, v98, v2
	v_exp_f32_e32 v98, v14
	v_sub_f32_e32 v14, v89, v2
	v_exp_f32_e32 v89, v14
	v_sub_f32_e32 v14, v106, v2
	v_sub_f32_e32 v9, v99, v2
	v_exp_f32_e32 v99, v14
	v_sub_f32_e32 v14, v90, v2
	v_sub_f32_e32 v10, v83, v2
	v_exp_f32_e32 v90, v14
	v_sub_f32_e32 v14, v107, v2
	v_sub_f32_e32 v3, v96, v2
	v_exp_f32_e32 v96, v10
	v_sub_f32_e32 v10, v100, v2
	v_exp_f32_e32 v100, v14
	v_sub_f32_e32 v14, v91, v2
	v_sub_f32_e32 v11, v84, v2
	v_exp_f32_e32 v91, v14
	v_sub_f32_e32 v14, v108, v2
	v_exp_f32_e32 v84, v11
	v_sub_f32_e32 v11, v101, v2
	v_exp_f32_e32 v101, v14
	v_sub_f32_e32 v14, v92, v2
	v_sub_f32_e32 v4, v80, v2
	v_sub_f32_e32 v12, v85, v2
	v_exp_f32_e32 v92, v14
	v_sub_f32_e32 v14, v109, v2
	v_exp_f32_e32 v3, v3
	v_exp_f32_e32 v4, v4
	v_sub_f32_e32 v6, v81, v2
	v_exp_f32_e32 v85, v12
	v_sub_f32_e32 v12, v102, v2
	v_exp_f32_e32 v102, v14
	v_sub_f32_e32 v14, v93, v2
	v_exp_f32_e32 v5, v5
	v_exp_f32_e32 v6, v6
	v_sub_f32_e32 v8, v82, v2
	v_sub_f32_e32 v13, v86, v2
	v_exp_f32_e32 v93, v14
	v_sub_f32_e32 v14, v110, v2
	v_exp_f32_e32 v7, v7
	v_exp_f32_e32 v8, v8
	v_exp_f32_e32 v86, v13
	v_sub_f32_e32 v13, v103, v2
	v_exp_f32_e32 v103, v14
	v_sub_f32_e32 v14, v94, v2
	v_exp_f32_e32 v9, v9
	v_exp_f32_e32 v94, v14
	v_sub_f32_e32 v14, v111, v2
	v_sub_f32_e32 v2, v95, v2
	v_exp_f32_e32 v10, v10
	v_exp_f32_e32 v95, v2
	v_add_f32_e32 v2, v3, v4
	v_exp_f32_e32 v11, v11
	v_exp_f32_e32 v104, v14
	v_add_f32_e32 v2, 0, v2
	v_add_f32_e32 v14, v5, v6
	v_exp_f32_e32 v12, v12
	v_add_f32_e32 v2, v14, v2
	v_add_f32_e32 v14, v7, v8
	v_exp_f32_e32 v13, v13
	v_add_f32_e32 v2, v14, v2
	v_add_f32_e32 v14, v9, v96
	v_add_f32_e32 v2, v14, v2
	v_add_f32_e32 v14, v10, v84
	v_add_f32_e32 v2, v14, v2
	v_add_f32_e32 v14, v11, v85
	v_add_f32_e32 v2, v14, v2
	v_add_f32_e32 v14, v12, v86
	v_add_f32_e32 v2, v14, v2
	v_add_f32_e32 v14, v13, v87
	v_add_f32_e32 v2, v14, v2
	v_add_f32_e32 v14, v97, v88
	v_add_f32_e32 v2, v14, v2
	v_add_f32_e32 v14, v98, v89
	v_add_f32_e32 v2, v14, v2
	v_add_f32_e32 v14, v99, v90
	v_add_f32_e32 v2, v14, v2
	v_add_f32_e32 v14, v100, v91
	v_add_f32_e32 v2, v14, v2
	v_add_f32_e32 v14, v101, v92
	v_add_f32_e32 v2, v14, v2
	v_add_f32_e32 v14, v102, v93
	v_add_f32_e32 v2, v14, v2
	v_add_f32_e32 v14, v103, v94
	v_exp_f32_e32 v0, v0
	v_add_f32_e32 v2, v14, v2
	v_add_f32_e32 v14, v104, v95
	v_add_f32_e32 v14, v14, v2
	v_mov_b32_e32 v15, v14
	v_cvt_pk_bf16_f32 v80, v3, v5
	v_cvt_pk_bf16_f32 v81, v7, v9
	v_cvt_pk_bf16_f32 v82, v10, v11
	v_cvt_pk_bf16_f32 v83, v12, v13
	v_cvt_pk_bf16_f32 v10, v97, v98
	v_cvt_pk_bf16_f32 v11, v99, v100
	v_cvt_pk_bf16_f32 v12, v101, v102
	v_cvt_pk_bf16_f32 v13, v103, v104
	v_cvt_pk_bf16_f32 v6, v4, v6
	v_cvt_pk_bf16_f32 v7, v8, v96
	v_cvt_pk_bf16_f32 v8, v84, v85
	v_cvt_pk_bf16_f32 v9, v86, v87
	v_cvt_pk_bf16_f32 v2, v88, v89
	v_cvt_pk_bf16_f32 v3, v90, v91
	v_cvt_pk_bf16_f32 v4, v92, v93
	v_cvt_pk_bf16_f32 v5, v94, v95
	s_nop 1
	v_permlane32_swap_b32_e32 v14, v15
	v_permlane32_swap_b32_e32 v80, v82
	v_permlane32_swap_b32_e32 v81, v83
	v_permlane32_swap_b32_e32 v10, v12
	v_permlane32_swap_b32_e32 v11, v13
	v_permlane32_swap_b32_e32 v6, v8
	v_permlane32_swap_b32_e32 v7, v9
	v_permlane32_swap_b32_e32 v2, v4
	v_permlane32_swap_b32_e32 v3, v5
	s_cbranch_vccnz .LBB0_878
	s_and_saveexec_b64 s[4:5], s[0:1]
	ds_write_b32 v152, v0 offset:128
	s_or_b64 exec, exec, s[4:5]
	s_waitcnt lgkmcnt(0)
	v_add_u32_e32 v96, v150, v151
	ds_read_b128 v[84:87], v96 offset:224
	ds_read_b128 v[88:91], v96 offset:192
	ds_read_b128 v[92:95], v96 offset:160
	ds_read_b128 v[96:99], v96 offset:128
	s_waitcnt lgkmcnt(3)
	v_pk_mul_f32 v[76:77], v[76:77], v[84:85]
	s_waitcnt lgkmcnt(2)
	v_pk_mul_f32 v[72:73], v[72:73], v[88:89]
	s_waitcnt lgkmcnt(1)
	v_pk_mul_f32 v[68:69], v[68:69], v[92:93]
	v_pk_mul_f32 v[78:79], v[78:79], v[86:87]
	v_pk_mul_f32 v[74:75], v[74:75], v[90:91]
	v_pk_mul_f32 v[70:71], v[70:71], v[94:95]
	s_waitcnt lgkmcnt(0)
	v_pk_mul_f32 v[66:67], v[66:67], v[98:99]
	v_pk_mul_f32 v[64:65], v[64:65], v[96:97]
	v_pk_mul_f32 v[60:61], v[60:61], v[84:85]
	v_pk_mul_f32 v[56:57], v[56:57], v[88:89]
	v_pk_mul_f32 v[52:53], v[52:53], v[92:93]
	v_pk_mul_f32 v[62:63], v[62:63], v[86:87]
	v_pk_mul_f32 v[58:59], v[58:59], v[90:91]
	v_pk_mul_f32 v[54:55], v[54:55], v[94:95]
	v_pk_mul_f32 v[50:51], v[50:51], v[98:99]
	v_pk_mul_f32 v[48:49], v[48:49], v[96:97]
	v_pk_mul_f32 v[44:45], v[44:45], v[84:85]
	v_pk_mul_f32 v[40:41], v[40:41], v[88:89]
	v_pk_mul_f32 v[36:37], v[36:37], v[92:93]
	v_pk_mul_f32 v[46:47], v[46:47], v[86:87]
	v_pk_mul_f32 v[42:43], v[42:43], v[90:91]
	v_pk_mul_f32 v[38:39], v[38:39], v[94:95]
	v_pk_mul_f32 v[34:35], v[34:35], v[98:99]
	v_pk_mul_f32 v[32:33], v[32:33], v[96:97]
	v_pk_mul_f32 v[28:29], v[28:29], v[84:85]
	v_pk_mul_f32 v[24:25], v[24:25], v[88:89]
	v_pk_mul_f32 v[20:21], v[20:21], v[92:93]
	v_pk_mul_f32 v[30:31], v[30:31], v[86:87]
	v_pk_mul_f32 v[26:27], v[26:27], v[90:91]
	v_pk_mul_f32 v[22:23], v[22:23], v[94:95]
	v_pk_mul_f32 v[18:19], v[18:19], v[98:99]
	v_pk_mul_f32 v[16:17], v[16:17], v[96:97]

.LBB0_1000:
	s_and_b64 s[28:29], s[18:19], s[24:25]
	s_and_saveexec_b64 s[4:5], s[28:29]
	s_cbranch_execz .LBB0_1006
	v_max_f32_e32 v0, v80, v81
	v_max3_f32 v0, v0, v82, v83
	v_max3_f32 v0, v0, v84, v85
	v_max3_f32 v0, v0, v86, v87
	v_max3_f32 v0, v0, v88, v89
	v_max3_f32 v0, v0, v90, v91
	v_max3_f32 v0, v0, v92, v93
	v_max3_f32 v0, v0, v94, v95
	v_max3_f32 v0, v0, v96, v97
	v_max3_f32 v0, v0, v98, v99
	v_max3_f32 v0, v0, v100, v101
	v_max3_f32 v0, v0, v102, v103
	v_max3_f32 v0, v0, v104, v105
	v_max3_f32 v0, v0, v106, v107
	v_max3_f32 v0, v0, v108, v109
	v_max3_f32 v0, v0, v110, v111
	v_mov_b32_e32 v2, v0
	s_nop 1
	v_permlane32_swap_b32_e32 v0, v2
	v_max_f32_e32 v0, v0, v2
	v_sub_f32_e32 v2, v0, v186
	v_cmp_ge_f32_e32 vcc, s86, v2
	s_cmp_eq_u64 vcc, exec
	v_max_f32_e32 v2, v186, v0
	s_cselect_b64 vcc, -1, 0
	v_sub_f32_e32 v0, v186, v2
	v_cndmask_b32_e32 v186, v2, v186, vcc
	v_sub_f32_e32 v2, v80, v186
	v_exp_f32_e32 v80, v2
	v_sub_f32_e32 v2, v96, v186
	v_exp_f32_e32 v96, v2
	v_sub_f32_e32 v2, v81, v186
	v_exp_f32_e32 v81, v2
	v_sub_f32_e32 v2, v97, v186
	v_exp_f32_e32 v97, v2
	v_sub_f32_e32 v2, v82, v186
	v_exp_f32_e32 v82, v2
	v_sub_f32_e32 v2, v98, v186
	v_exp_f32_e32 v98, v2
	v_sub_f32_e32 v2, v83, v186
	v_exp_f32_e32 v83, v2
	v_sub_f32_e32 v2, v99, v186
	v_exp_f32_e32 v99, v2
	v_sub_f32_e32 v2, v84, v186
	v_exp_f32_e32 v84, v2
	v_sub_f32_e32 v2, v100, v186
	v_exp_f32_e32 v100, v2
	v_sub_f32_e32 v2, v85, v186
	v_exp_f32_e32 v85, v2
	v_sub_f32_e32 v2, v101, v186
	v_exp_f32_e32 v101, v2
	v_sub_f32_e32 v2, v86, v186
	v_exp_f32_e32 v86, v2
	v_sub_f32_e32 v2, v102, v186
	v_exp_f32_e32 v102, v2
	v_sub_f32_e32 v2, v87, v186
	v_exp_f32_e32 v87, v2
	v_sub_f32_e32 v2, v103, v186
	v_exp_f32_e32 v103, v2
	v_sub_f32_e32 v2, v88, v186
	v_exp_f32_e32 v88, v2
	v_sub_f32_e32 v2, v104, v186
	v_exp_f32_e32 v104, v2
	v_sub_f32_e32 v2, v89, v186
	v_exp_f32_e32 v89, v2
	v_sub_f32_e32 v2, v105, v186
	v_exp_f32_e32 v105, v2
	v_sub_f32_e32 v2, v90, v186
	v_exp_f32_e32 v90, v2
	v_sub_f32_e32 v2, v106, v186
	v_exp_f32_e32 v106, v2
	v_sub_f32_e32 v2, v91, v186
	v_exp_f32_e32 v91, v2
	v_sub_f32_e32 v2, v107, v186
	v_exp_f32_e32 v107, v2
	v_sub_f32_e32 v2, v92, v186
	v_exp_f32_e32 v92, v2
	v_sub_f32_e32 v2, v108, v186
	v_exp_f32_e32 v108, v2
	v_sub_f32_e32 v2, v93, v186
	v_exp_f32_e32 v93, v2
	v_sub_f32_e32 v2, v109, v186
	v_exp_f32_e32 v109, v2
	v_sub_f32_e32 v2, v94, v186
	v_exp_f32_e32 v94, v2
	v_sub_f32_e32 v2, v110, v186
	v_exp_f32_e32 v110, v2
	v_sub_f32_e32 v2, v95, v186
	v_exp_f32_e32 v95, v2
	v_sub_f32_e32 v2, v111, v186
	v_exp_f32_e32 v111, v2
	v_add_f32_e32 v2, v80, v96
	v_add_f32_e32 v2, 0, v2
	v_add_f32_e32 v3, v81, v97
	v_add_f32_e32 v2, v3, v2
	v_add_f32_e32 v3, v82, v98
	v_add_f32_e32 v2, v3, v2
	v_add_f32_e32 v3, v83, v99
	v_add_f32_e32 v2, v3, v2
	v_add_f32_e32 v3, v84, v100
	v_add_f32_e32 v2, v3, v2
	v_add_f32_e32 v3, v85, v101
	v_add_f32_e32 v2, v3, v2
	v_add_f32_e32 v3, v86, v102
	v_add_f32_e32 v2, v3, v2
	v_add_f32_e32 v3, v87, v103
	v_add_f32_e32 v2, v3, v2
	v_add_f32_e32 v3, v88, v104
	v_add_f32_e32 v2, v3, v2
	v_add_f32_e32 v3, v89, v105
	v_add_f32_e32 v2, v3, v2
	v_add_f32_e32 v3, v90, v106
	v_add_f32_e32 v2, v3, v2
	v_add_f32_e32 v3, v91, v107
	v_add_f32_e32 v2, v3, v2
	v_add_f32_e32 v3, v92, v108
	v_add_f32_e32 v2, v3, v2
	v_add_f32_e32 v3, v93, v109
	v_add_f32_e32 v2, v3, v2
	v_add_f32_e32 v3, v94, v110
	v_exp_f32_e32 v0, v0
	v_add_f32_e32 v2, v3, v2
	v_add_f32_e32 v3, v95, v111
	v_add_f32_e32 v14, v3, v2
	v_mov_b32_e32 v15, v14
	v_cvt_pk_bf16_f32 v160, v80, v81
	v_cvt_pk_bf16_f32 v161, v82, v83
	v_cvt_pk_bf16_f32 v162, v84, v85
	v_cvt_pk_bf16_f32 v163, v86, v87
	v_cvt_pk_bf16_f32 v10, v88, v89
	v_cvt_pk_bf16_f32 v11, v90, v91
	v_cvt_pk_bf16_f32 v12, v92, v93
	v_cvt_pk_bf16_f32 v13, v94, v95
	v_cvt_pk_bf16_f32 v6, v96, v97
	v_cvt_pk_bf16_f32 v7, v98, v99
	v_cvt_pk_bf16_f32 v8, v100, v101
	v_cvt_pk_bf16_f32 v9, v102, v103
	v_cvt_pk_bf16_f32 v2, v104, v105
	v_cvt_pk_bf16_f32 v3, v106, v107
	v_cvt_pk_bf16_f32 v4, v108, v109
	v_cvt_pk_bf16_f32 v5, v110, v111
	s_nop 1
	v_permlane32_swap_b32_e32 v14, v15
	v_permlane32_swap_b32_e32 v160, v162
	v_permlane32_swap_b32_e32 v161, v163
	v_permlane32_swap_b32_e32 v10, v12
	v_permlane32_swap_b32_e32 v11, v13
	v_permlane32_swap_b32_e32 v6, v8
	v_permlane32_swap_b32_e32 v7, v9
	v_permlane32_swap_b32_e32 v2, v4
	v_permlane32_swap_b32_e32 v3, v5
	s_cbranch_vccnz .LBB0_1005
	s_and_saveexec_b64 s[28:29], s[0:1]
	ds_write_b32 v179, v0 offset:128
	s_or_b64 exec, exec, s[28:29]
	s_waitcnt lgkmcnt(0)
	v_add_u32_e32 v173, v176, v177
	ds_read_b128 v[206:209], v173 offset:224
	ds_read_b128 v[216:219], v173 offset:192
	ds_read_b128 v[220:223], v173 offset:160
	ds_read_b128 v[224:227], v173 offset:128
	s_waitcnt lgkmcnt(0)
	v_pk_mul_f32 v[76:77], v[76:77], v[206:207]
	v_pk_mul_f32 v[72:73], v[72:73], v[216:217]
	v_pk_mul_f32 v[68:69], v[68:69], v[220:221]
	v_pk_mul_f32 v[78:79], v[78:79], v[208:209]
	v_pk_mul_f32 v[74:75], v[74:75], v[218:219]
	v_pk_mul_f32 v[70:71], v[70:71], v[222:223]
	v_pk_mul_f32 v[66:67], v[66:67], v[226:227]
	v_pk_mul_f32 v[64:65], v[64:65], v[224:225]
	v_pk_mul_f32 v[60:61], v[60:61], v[206:207]
	v_pk_mul_f32 v[56:57], v[56:57], v[216:217]
	v_pk_mul_f32 v[52:53], v[52:53], v[220:221]
	v_pk_mul_f32 v[62:63], v[62:63], v[208:209]
	v_pk_mul_f32 v[58:59], v[58:59], v[218:219]
	v_pk_mul_f32 v[54:55], v[54:55], v[222:223]
	v_pk_mul_f32 v[50:51], v[50:51], v[226:227]
	v_pk_mul_f32 v[48:49], v[48:49], v[224:225]
	v_pk_mul_f32 v[44:45], v[44:45], v[206:207]
	v_pk_mul_f32 v[40:41], v[40:41], v[216:217]
	v_pk_mul_f32 v[36:37], v[36:37], v[220:221]
	v_pk_mul_f32 v[46:47], v[46:47], v[208:209]
	v_pk_mul_f32 v[42:43], v[42:43], v[218:219]
	v_pk_mul_f32 v[38:39], v[38:39], v[222:223]
	v_pk_mul_f32 v[34:35], v[34:35], v[226:227]
	v_pk_mul_f32 v[32:33], v[32:33], v[224:225]
	v_pk_mul_f32 v[28:29], v[28:29], v[206:207]
	v_pk_mul_f32 v[24:25], v[24:25], v[216:217]
	v_pk_mul_f32 v[20:21], v[20:21], v[220:221]
	v_pk_mul_f32 v[30:31], v[30:31], v[208:209]
	v_pk_mul_f32 v[26:27], v[26:27], v[218:219]
	v_pk_mul_f32 v[22:23], v[22:23], v[222:223]
	v_pk_mul_f32 v[18:19], v[18:19], v[226:227]
	v_pk_mul_f32 v[16:17], v[16:17], v[224:225]

.LBB0_1010:
	s_or_b64 exec, exec, s[28:29]
	s_andn2_b64 s[4:5], s[24:25], exec
	s_and_b64 s[24:25], vcc, exec
	s_and_b64 s[28:29], vcc, s[20:21]
	s_or_b64 s[24:25], s[4:5], s[24:25]
	s_and_saveexec_b64 s[4:5], s[28:29]
	s_cbranch_execz .LBB0_1017
	v_max_f32_e32 v0, v80, v81
	v_max3_f32 v0, v0, v82, v83
	v_max3_f32 v0, v0, v84, v85
	v_max3_f32 v0, v0, v86, v87
	v_max3_f32 v0, v0, v88, v89
	v_max3_f32 v0, v0, v90, v91
	v_max3_f32 v0, v0, v92, v93
	v_max3_f32 v0, v0, v94, v95
	v_max3_f32 v0, v0, v96, v97
	v_max3_f32 v0, v0, v98, v99
	v_max3_f32 v0, v0, v100, v101
	v_max3_f32 v0, v0, v102, v103
	v_max3_f32 v0, v0, v104, v105
	v_max3_f32 v0, v0, v106, v107
	v_max3_f32 v0, v0, v108, v109
	v_max3_f32 v0, v0, v110, v111
	v_mov_b32_e32 v2, v0
	s_nop 1
	v_permlane32_swap_b32_e32 v0, v2
	v_max_f32_e32 v0, v0, v2
	v_sub_f32_e32 v2, v0, v186
	v_cmp_ge_f32_e32 vcc, s86, v2
	s_cmp_eq_u64 vcc, exec
	v_max_f32_e32 v2, v186, v0
	s_cselect_b64 vcc, -1, 0
	v_sub_f32_e32 v0, v186, v2
	v_cndmask_b32_e32 v186, v2, v186, vcc
	v_sub_f32_e32 v2, v80, v186
	v_exp_f32_e32 v80, v2
	v_sub_f32_e32 v2, v96, v186
	v_exp_f32_e32 v96, v2
	v_sub_f32_e32 v2, v81, v186
	v_exp_f32_e32 v81, v2
	v_sub_f32_e32 v2, v97, v186
	v_exp_f32_e32 v97, v2
	v_sub_f32_e32 v2, v82, v186
	v_exp_f32_e32 v82, v2
	v_sub_f32_e32 v2, v98, v186
	v_exp_f32_e32 v98, v2
	v_sub_f32_e32 v2, v83, v186
	v_exp_f32_e32 v83, v2
	v_sub_f32_e32 v2, v99, v186
	v_exp_f32_e32 v99, v2
	v_sub_f32_e32 v2, v84, v186
	v_exp_f32_e32 v84, v2
	v_sub_f32_e32 v2, v100, v186
	v_exp_f32_e32 v100, v2
	v_sub_f32_e32 v2, v85, v186
	v_exp_f32_e32 v85, v2
	v_sub_f32_e32 v2, v101, v186
	v_exp_f32_e32 v101, v2
	v_sub_f32_e32 v2, v86, v186
	v_exp_f32_e32 v86, v2
	v_sub_f32_e32 v2, v102, v186
	v_exp_f32_e32 v102, v2
	v_sub_f32_e32 v2, v87, v186
	v_exp_f32_e32 v87, v2
	v_sub_f32_e32 v2, v103, v186
	v_exp_f32_e32 v103, v2
	v_sub_f32_e32 v2, v88, v186
	v_exp_f32_e32 v88, v2
	v_sub_f32_e32 v2, v104, v186
	v_exp_f32_e32 v104, v2
	v_sub_f32_e32 v2, v89, v186
	v_exp_f32_e32 v89, v2
	v_sub_f32_e32 v2, v105, v186
	v_exp_f32_e32 v105, v2
	v_sub_f32_e32 v2, v90, v186
	v_exp_f32_e32 v90, v2
	v_sub_f32_e32 v2, v106, v186
	v_exp_f32_e32 v106, v2
	v_sub_f32_e32 v2, v91, v186
	v_exp_f32_e32 v91, v2
	v_sub_f32_e32 v2, v107, v186
	v_exp_f32_e32 v107, v2
	v_sub_f32_e32 v2, v92, v186
	v_exp_f32_e32 v92, v2
	v_sub_f32_e32 v2, v108, v186
	v_exp_f32_e32 v108, v2
	v_sub_f32_e32 v2, v93, v186
	v_exp_f32_e32 v93, v2
	v_sub_f32_e32 v2, v109, v186
	v_exp_f32_e32 v109, v2
	v_sub_f32_e32 v2, v94, v186
	v_exp_f32_e32 v94, v2
	v_sub_f32_e32 v2, v110, v186
	v_exp_f32_e32 v110, v2
	v_sub_f32_e32 v2, v95, v186
	v_exp_f32_e32 v95, v2
	v_sub_f32_e32 v2, v111, v186
	v_exp_f32_e32 v111, v2
	v_add_f32_e32 v2, v80, v96
	v_add_f32_e32 v2, 0, v2
	v_add_f32_e32 v3, v81, v97
	v_add_f32_e32 v2, v3, v2
	v_add_f32_e32 v3, v82, v98
	v_add_f32_e32 v2, v3, v2
	v_add_f32_e32 v3, v83, v99
	v_add_f32_e32 v2, v3, v2
	v_add_f32_e32 v3, v84, v100
	v_add_f32_e32 v2, v3, v2
	v_add_f32_e32 v3, v85, v101
	v_add_f32_e32 v2, v3, v2
	v_add_f32_e32 v3, v86, v102
	v_add_f32_e32 v2, v3, v2
	v_add_f32_e32 v3, v87, v103
	v_add_f32_e32 v2, v3, v2
	v_add_f32_e32 v3, v88, v104
	v_add_f32_e32 v2, v3, v2
	v_add_f32_e32 v3, v89, v105
	v_add_f32_e32 v2, v3, v2
	v_add_f32_e32 v3, v90, v106
	v_add_f32_e32 v2, v3, v2
	v_add_f32_e32 v3, v91, v107
	v_add_f32_e32 v2, v3, v2
	v_add_f32_e32 v3, v92, v108
	v_add_f32_e32 v2, v3, v2
	v_add_f32_e32 v3, v93, v109
	v_add_f32_e32 v2, v3, v2
	v_add_f32_e32 v3, v94, v110
	v_exp_f32_e32 v0, v0
	v_add_f32_e32 v2, v3, v2
	v_add_f32_e32 v3, v95, v111
	v_add_f32_e32 v14, v3, v2
	v_mov_b32_e32 v15, v14
	v_cvt_pk_bf16_f32 v160, v80, v81
	v_cvt_pk_bf16_f32 v161, v82, v83
	v_cvt_pk_bf16_f32 v162, v84, v85
	v_cvt_pk_bf16_f32 v163, v86, v87
	v_cvt_pk_bf16_f32 v10, v88, v89
	v_cvt_pk_bf16_f32 v11, v90, v91
	v_cvt_pk_bf16_f32 v12, v92, v93
	v_cvt_pk_bf16_f32 v13, v94, v95
	v_cvt_pk_bf16_f32 v6, v96, v97
	v_cvt_pk_bf16_f32 v7, v98, v99
	v_cvt_pk_bf16_f32 v8, v100, v101
	v_cvt_pk_bf16_f32 v9, v102, v103
	v_cvt_pk_bf16_f32 v2, v104, v105
	v_cvt_pk_bf16_f32 v3, v106, v107
	v_cvt_pk_bf16_f32 v4, v108, v109
	v_cvt_pk_bf16_f32 v5, v110, v111
	s_nop 1
	v_permlane32_swap_b32_e32 v14, v15
	v_permlane32_swap_b32_e32 v160, v162
	v_permlane32_swap_b32_e32 v161, v163
	v_permlane32_swap_b32_e32 v10, v12
	v_permlane32_swap_b32_e32 v11, v13
	v_permlane32_swap_b32_e32 v6, v8
	v_permlane32_swap_b32_e32 v7, v9
	v_permlane32_swap_b32_e32 v2, v4
	v_permlane32_swap_b32_e32 v3, v5
	s_cbranch_vccnz .LBB0_1015
	s_and_saveexec_b64 s[28:29], s[0:1]
	ds_write_b32 v179, v0 offset:128
	s_or_b64 exec, exec, s[28:29]
	s_waitcnt lgkmcnt(0)
	v_add_u32_e32 v173, v176, v177
	ds_read_b128 v[206:209], v173 offset:224
	ds_read_b128 v[216:219], v173 offset:192
	ds_read_b128 v[220:223], v173 offset:160
	ds_read_b128 v[224:227], v173 offset:128
	s_waitcnt lgkmcnt(0)
	v_pk_mul_f32 v[76:77], v[76:77], v[206:207]
	v_pk_mul_f32 v[72:73], v[72:73], v[216:217]
	v_pk_mul_f32 v[68:69], v[68:69], v[220:221]
	v_pk_mul_f32 v[78:79], v[78:79], v[208:209]
	v_pk_mul_f32 v[74:75], v[74:75], v[218:219]
	v_pk_mul_f32 v[70:71], v[70:71], v[222:223]
	v_pk_mul_f32 v[66:67], v[66:67], v[226:227]
	v_pk_mul_f32 v[64:65], v[64:65], v[224:225]
	v_pk_mul_f32 v[60:61], v[60:61], v[206:207]
	v_pk_mul_f32 v[56:57], v[56:57], v[216:217]
	v_pk_mul_f32 v[52:53], v[52:53], v[220:221]
	v_pk_mul_f32 v[62:63], v[62:63], v[208:209]
	v_pk_mul_f32 v[58:59], v[58:59], v[218:219]
	v_pk_mul_f32 v[54:55], v[54:55], v[222:223]
	v_pk_mul_f32 v[50:51], v[50:51], v[226:227]
	v_pk_mul_f32 v[48:49], v[48:49], v[224:225]
	v_pk_mul_f32 v[44:45], v[44:45], v[206:207]
	v_pk_mul_f32 v[40:41], v[40:41], v[216:217]
	v_pk_mul_f32 v[36:37], v[36:37], v[220:221]
	v_pk_mul_f32 v[46:47], v[46:47], v[208:209]
	v_pk_mul_f32 v[42:43], v[42:43], v[218:219]
	v_pk_mul_f32 v[38:39], v[38:39], v[222:223]
	v_pk_mul_f32 v[34:35], v[34:35], v[226:227]
	v_pk_mul_f32 v[32:33], v[32:33], v[224:225]
	v_pk_mul_f32 v[28:29], v[28:29], v[206:207]
	v_pk_mul_f32 v[24:25], v[24:25], v[216:217]
	v_pk_mul_f32 v[20:21], v[20:21], v[220:221]
	v_pk_mul_f32 v[30:31], v[30:31], v[208:209]
	v_pk_mul_f32 v[26:27], v[26:27], v[218:219]
	v_pk_mul_f32 v[22:23], v[22:23], v[222:223]
	v_pk_mul_f32 v[18:19], v[18:19], v[226:227]
	v_pk_mul_f32 v[16:17], v[16:17], v[224:225]

.LBB0_1020:
	s_and_b64 s[18:19], s[18:19], s[24:25]
	s_and_saveexec_b64 s[4:5], s[18:19]
	s_cbranch_execz .LBB0_1026
	v_max_f32_e32 v0, v80, v81
	v_max3_f32 v0, v0, v82, v83
	v_max3_f32 v0, v0, v84, v85
	v_max3_f32 v0, v0, v86, v87
	v_max3_f32 v0, v0, v88, v89
	v_max3_f32 v0, v0, v90, v91
	v_max3_f32 v0, v0, v92, v93
	v_max3_f32 v0, v0, v94, v95
	v_max3_f32 v0, v0, v96, v97
	v_max3_f32 v0, v0, v98, v99
	v_max3_f32 v0, v0, v100, v101
	v_max3_f32 v0, v0, v102, v103
	v_max3_f32 v0, v0, v104, v105
	v_max3_f32 v0, v0, v106, v107
	v_max3_f32 v0, v0, v108, v109
	v_max3_f32 v0, v0, v110, v111
	v_mov_b32_e32 v2, v0
	s_nop 1
	v_permlane32_swap_b32_e32 v0, v2
	v_max_f32_e32 v0, v0, v2
	v_sub_f32_e32 v2, v0, v186
	v_cmp_ge_f32_e32 vcc, s86, v2
	s_cmp_eq_u64 vcc, exec
	v_max_f32_e32 v2, v186, v0
	s_cselect_b64 vcc, -1, 0
	v_sub_f32_e32 v0, v186, v2
	v_cndmask_b32_e32 v2, v2, v186, vcc
	v_sub_f32_e32 v10, v99, v2
	v_sub_f32_e32 v11, v100, v2
	v_sub_f32_e32 v12, v101, v2
	v_sub_f32_e32 v13, v102, v2
	v_sub_f32_e32 v14, v103, v2
	v_sub_f32_e32 v4, v96, v2
	v_exp_f32_e32 v96, v10
	v_sub_f32_e32 v10, v84, v2
	v_exp_f32_e32 v84, v11
	v_sub_f32_e32 v11, v85, v2
	v_exp_f32_e32 v85, v12
	v_sub_f32_e32 v12, v86, v2
	v_exp_f32_e32 v86, v13
	v_sub_f32_e32 v13, v87, v2
	v_exp_f32_e32 v87, v14
	v_sub_f32_e32 v14, v88, v2
	v_exp_f32_e32 v88, v14
	v_sub_f32_e32 v14, v104, v2
	v_sub_f32_e32 v6, v97, v2
	v_exp_f32_e32 v97, v14
	v_sub_f32_e32 v14, v89, v2
	v_exp_f32_e32 v89, v14
	v_sub_f32_e32 v14, v105, v2
	v_sub_f32_e32 v8, v98, v2
	v_exp_f32_e32 v98, v14
	v_sub_f32_e32 v14, v90, v2
	v_exp_f32_e32 v90, v14
	v_sub_f32_e32 v14, v106, v2
	v_exp_f32_e32 v99, v14
	v_sub_f32_e32 v14, v91, v2
	v_exp_f32_e32 v91, v14
	v_sub_f32_e32 v14, v107, v2
	v_exp_f32_e32 v100, v14
	v_sub_f32_e32 v14, v92, v2
	v_exp_f32_e32 v92, v14
	v_sub_f32_e32 v14, v108, v2
	v_sub_f32_e32 v3, v80, v2
	v_exp_f32_e32 v101, v14
	v_sub_f32_e32 v14, v93, v2
	v_exp_f32_e32 v3, v3
	v_exp_f32_e32 v4, v4
	v_sub_f32_e32 v5, v81, v2
	v_exp_f32_e32 v93, v14
	v_sub_f32_e32 v14, v109, v2
	v_exp_f32_e32 v5, v5
	v_exp_f32_e32 v6, v6
	v_sub_f32_e32 v7, v82, v2
	v_exp_f32_e32 v102, v14
	v_sub_f32_e32 v14, v94, v2
	v_exp_f32_e32 v7, v7
	v_exp_f32_e32 v8, v8
	v_sub_f32_e32 v9, v83, v2
	v_exp_f32_e32 v94, v14
	v_sub_f32_e32 v14, v110, v2
	v_exp_f32_e32 v9, v9
	v_exp_f32_e32 v103, v14
	v_sub_f32_e32 v14, v95, v2
	v_sub_f32_e32 v2, v111, v2
	v_exp_f32_e32 v10, v10
	v_exp_f32_e32 v104, v2
	v_add_f32_e32 v2, v3, v4
	v_exp_f32_e32 v11, v11
	v_exp_f32_e32 v95, v14
	v_add_f32_e32 v2, 0, v2
	v_add_f32_e32 v14, v5, v6
	v_exp_f32_e32 v12, v12
	v_add_f32_e32 v2, v14, v2
	v_add_f32_e32 v14, v7, v8
	v_exp_f32_e32 v13, v13
	v_add_f32_e32 v2, v14, v2
	v_add_f32_e32 v14, v9, v96
	v_add_f32_e32 v2, v14, v2
	v_add_f32_e32 v14, v10, v84
	v_add_f32_e32 v2, v14, v2
	v_add_f32_e32 v14, v11, v85
	v_add_f32_e32 v2, v14, v2
	v_add_f32_e32 v14, v12, v86
	v_add_f32_e32 v2, v14, v2
	v_add_f32_e32 v14, v13, v87
	v_add_f32_e32 v2, v14, v2
	v_add_f32_e32 v14, v88, v97
	v_add_f32_e32 v2, v14, v2
	v_add_f32_e32 v14, v89, v98
	v_add_f32_e32 v2, v14, v2
	v_add_f32_e32 v14, v90, v99
	v_add_f32_e32 v2, v14, v2
	v_add_f32_e32 v14, v91, v100
	v_add_f32_e32 v2, v14, v2
	v_add_f32_e32 v14, v92, v101
	v_add_f32_e32 v2, v14, v2
	v_add_f32_e32 v14, v93, v102
	v_add_f32_e32 v2, v14, v2
	v_add_f32_e32 v14, v94, v103
	v_exp_f32_e32 v0, v0
	v_add_f32_e32 v2, v14, v2
	v_add_f32_e32 v14, v95, v104
	v_add_f32_e32 v14, v14, v2
	v_mov_b32_e32 v15, v14
	v_cvt_pk_bf16_f32 v80, v3, v5
	v_cvt_pk_bf16_f32 v81, v7, v9
	v_cvt_pk_bf16_f32 v82, v10, v11
	v_cvt_pk_bf16_f32 v83, v12, v13
	v_cvt_pk_bf16_f32 v10, v88, v89
	v_cvt_pk_bf16_f32 v11, v90, v91
	v_cvt_pk_bf16_f32 v12, v92, v93
	v_cvt_pk_bf16_f32 v13, v94, v95
	v_cvt_pk_bf16_f32 v6, v4, v6
	v_cvt_pk_bf16_f32 v7, v8, v96
	v_cvt_pk_bf16_f32 v8, v84, v85
	v_cvt_pk_bf16_f32 v9, v86, v87
	v_cvt_pk_bf16_f32 v2, v97, v98
	v_cvt_pk_bf16_f32 v3, v99, v100
	v_cvt_pk_bf16_f32 v4, v101, v102
	v_cvt_pk_bf16_f32 v5, v103, v104
	s_nop 1
	v_permlane32_swap_b32_e32 v14, v15
	v_permlane32_swap_b32_e32 v80, v82
	v_permlane32_swap_b32_e32 v81, v83
	v_permlane32_swap_b32_e32 v10, v12
	v_permlane32_swap_b32_e32 v11, v13
	v_permlane32_swap_b32_e32 v6, v8
	v_permlane32_swap_b32_e32 v7, v9
	v_permlane32_swap_b32_e32 v2, v4
	v_permlane32_swap_b32_e32 v3, v5
	s_cbranch_vccnz .LBB0_1025
	s_and_saveexec_b64 s[18:19], s[0:1]
	ds_write_b32 v179, v0 offset:128
	s_or_b64 exec, exec, s[18:19]
	s_waitcnt lgkmcnt(0)
	v_add_u32_e32 v96, v176, v177
	ds_read_b128 v[84:87], v96 offset:224
	ds_read_b128 v[88:91], v96 offset:192
	ds_read_b128 v[92:95], v96 offset:160
	ds_read_b128 v[96:99], v96 offset:128
	s_waitcnt lgkmcnt(3)
	v_pk_mul_f32 v[76:77], v[76:77], v[84:85]
	s_waitcnt lgkmcnt(2)
	v_pk_mul_f32 v[72:73], v[72:73], v[88:89]
	s_waitcnt lgkmcnt(1)
	v_pk_mul_f32 v[68:69], v[68:69], v[92:93]
	v_pk_mul_f32 v[78:79], v[78:79], v[86:87]
	v_pk_mul_f32 v[74:75], v[74:75], v[90:91]
	v_pk_mul_f32 v[70:71], v[70:71], v[94:95]
	s_waitcnt lgkmcnt(0)
	v_pk_mul_f32 v[66:67], v[66:67], v[98:99]
	v_pk_mul_f32 v[64:65], v[64:65], v[96:97]
	v_pk_mul_f32 v[60:61], v[60:61], v[84:85]
	v_pk_mul_f32 v[56:57], v[56:57], v[88:89]
	v_pk_mul_f32 v[52:53], v[52:53], v[92:93]
	v_pk_mul_f32 v[62:63], v[62:63], v[86:87]
	v_pk_mul_f32 v[58:59], v[58:59], v[90:91]
	v_pk_mul_f32 v[54:55], v[54:55], v[94:95]
	v_pk_mul_f32 v[50:51], v[50:51], v[98:99]
	v_pk_mul_f32 v[48:49], v[48:49], v[96:97]
	v_pk_mul_f32 v[44:45], v[44:45], v[84:85]
	v_pk_mul_f32 v[40:41], v[40:41], v[88:89]
	v_pk_mul_f32 v[36:37], v[36:37], v[92:93]
	v_pk_mul_f32 v[46:47], v[46:47], v[86:87]
	v_pk_mul_f32 v[42:43], v[42:43], v[90:91]
	v_pk_mul_f32 v[38:39], v[38:39], v[94:95]
	v_pk_mul_f32 v[34:35], v[34:35], v[98:99]
	v_pk_mul_f32 v[32:33], v[32:33], v[96:97]
	v_pk_mul_f32 v[28:29], v[28:29], v[84:85]
	v_pk_mul_f32 v[24:25], v[24:25], v[88:89]
	v_pk_mul_f32 v[20:21], v[20:21], v[92:93]
	v_pk_mul_f32 v[30:31], v[30:31], v[86:87]
	v_pk_mul_f32 v[26:27], v[26:27], v[90:91]
	v_pk_mul_f32 v[22:23], v[22:23], v[94:95]
	v_pk_mul_f32 v[18:19], v[18:19], v[98:99]
	v_pk_mul_f32 v[16:17], v[16:17], v[96:97]

.LBB0_1042:
	s_and_b64 s[20:21], s[14:15], s[6:7]
	s_and_saveexec_b64 s[6:7], s[20:21]
	s_cbranch_execz .LBB0_1048
	v_max_f32_e32 v0, v80, v81
	v_max3_f32 v0, v0, v82, v83
	v_max3_f32 v0, v0, v84, v85
	v_max3_f32 v0, v0, v86, v87
	v_max3_f32 v0, v0, v88, v89
	v_max3_f32 v0, v0, v90, v91
	v_max3_f32 v0, v0, v92, v93
	v_max3_f32 v0, v0, v94, v95
	v_max3_f32 v0, v0, v96, v97
	v_max3_f32 v0, v0, v98, v99
	v_max3_f32 v0, v0, v100, v101
	v_max3_f32 v0, v0, v102, v103
	v_max3_f32 v0, v0, v104, v105
	v_max3_f32 v0, v0, v106, v107
	v_max3_f32 v0, v0, v108, v109
	v_max3_f32 v0, v0, v110, v111
	v_mov_b32_e32 v2, v0
	s_nop 1
	v_permlane32_swap_b32_e32 v0, v2
	v_max_f32_e32 v0, v0, v2
	v_sub_f32_e32 v2, v0, v186
	v_cmp_ge_f32_e32 vcc, s86, v2
	s_cmp_eq_u64 vcc, exec
	v_max_f32_e32 v2, v186, v0
	s_cselect_b64 vcc, -1, 0
	v_sub_f32_e32 v0, v186, v2
	v_cndmask_b32_e32 v186, v2, v186, vcc
	v_sub_f32_e32 v2, v80, v186
	v_exp_f32_e32 v80, v2
	v_sub_f32_e32 v2, v96, v186
	v_exp_f32_e32 v96, v2
	v_sub_f32_e32 v2, v81, v186
	v_exp_f32_e32 v81, v2
	v_sub_f32_e32 v2, v97, v186
	v_exp_f32_e32 v97, v2
	v_sub_f32_e32 v2, v82, v186
	v_exp_f32_e32 v82, v2
	v_sub_f32_e32 v2, v98, v186
	v_exp_f32_e32 v98, v2
	v_sub_f32_e32 v2, v83, v186
	v_exp_f32_e32 v83, v2
	v_sub_f32_e32 v2, v99, v186
	v_exp_f32_e32 v99, v2
	v_sub_f32_e32 v2, v84, v186
	v_exp_f32_e32 v84, v2
	v_sub_f32_e32 v2, v100, v186
	v_exp_f32_e32 v100, v2
	v_sub_f32_e32 v2, v85, v186
	v_exp_f32_e32 v85, v2
	v_sub_f32_e32 v2, v101, v186
	v_exp_f32_e32 v101, v2
	v_sub_f32_e32 v2, v86, v186
	v_exp_f32_e32 v86, v2
	v_sub_f32_e32 v2, v102, v186
	v_exp_f32_e32 v102, v2
	v_sub_f32_e32 v2, v87, v186
	v_exp_f32_e32 v87, v2
	v_sub_f32_e32 v2, v103, v186
	v_exp_f32_e32 v103, v2
	v_sub_f32_e32 v2, v88, v186
	v_exp_f32_e32 v88, v2
	v_sub_f32_e32 v2, v104, v186
	v_exp_f32_e32 v104, v2
	v_sub_f32_e32 v2, v89, v186
	v_exp_f32_e32 v89, v2
	v_sub_f32_e32 v2, v105, v186
	v_exp_f32_e32 v105, v2
	v_sub_f32_e32 v2, v90, v186
	v_exp_f32_e32 v90, v2
	v_sub_f32_e32 v2, v106, v186
	v_exp_f32_e32 v106, v2
	v_sub_f32_e32 v2, v91, v186
	v_exp_f32_e32 v91, v2
	v_sub_f32_e32 v2, v107, v186
	v_exp_f32_e32 v107, v2
	v_sub_f32_e32 v2, v92, v186
	v_exp_f32_e32 v92, v2
	v_sub_f32_e32 v2, v108, v186
	v_exp_f32_e32 v108, v2
	v_sub_f32_e32 v2, v93, v186
	v_exp_f32_e32 v93, v2
	v_sub_f32_e32 v2, v109, v186
	v_exp_f32_e32 v109, v2
	v_sub_f32_e32 v2, v94, v186
	v_exp_f32_e32 v94, v2
	v_sub_f32_e32 v2, v110, v186
	v_exp_f32_e32 v110, v2
	v_sub_f32_e32 v2, v95, v186
	v_exp_f32_e32 v95, v2
	v_sub_f32_e32 v2, v111, v186
	v_exp_f32_e32 v111, v2
	v_add_f32_e32 v2, v80, v96
	v_add_f32_e32 v2, 0, v2
	v_add_f32_e32 v3, v81, v97
	v_add_f32_e32 v2, v3, v2
	v_add_f32_e32 v3, v82, v98
	v_add_f32_e32 v2, v3, v2
	v_add_f32_e32 v3, v83, v99
	v_add_f32_e32 v2, v3, v2
	v_add_f32_e32 v3, v84, v100
	v_add_f32_e32 v2, v3, v2
	v_add_f32_e32 v3, v85, v101
	v_add_f32_e32 v2, v3, v2
	v_add_f32_e32 v3, v86, v102
	v_add_f32_e32 v2, v3, v2
	v_add_f32_e32 v3, v87, v103
	v_add_f32_e32 v2, v3, v2
	v_add_f32_e32 v3, v88, v104
	v_add_f32_e32 v2, v3, v2
	v_add_f32_e32 v3, v89, v105
	v_add_f32_e32 v2, v3, v2
	v_add_f32_e32 v3, v90, v106
	v_add_f32_e32 v2, v3, v2
	v_add_f32_e32 v3, v91, v107
	v_add_f32_e32 v2, v3, v2
	v_add_f32_e32 v3, v92, v108
	v_add_f32_e32 v2, v3, v2
	v_add_f32_e32 v3, v93, v109
	v_add_f32_e32 v2, v3, v2
	v_add_f32_e32 v3, v94, v110
	v_exp_f32_e32 v0, v0
	v_add_f32_e32 v2, v3, v2
	v_add_f32_e32 v3, v95, v111
	v_add_f32_e32 v14, v3, v2
	v_mov_b32_e32 v15, v14
	v_cvt_pk_bf16_f32 v144, v80, v81
	v_cvt_pk_bf16_f32 v145, v82, v83
	v_cvt_pk_bf16_f32 v146, v84, v85
	v_cvt_pk_bf16_f32 v147, v86, v87
	v_cvt_pk_bf16_f32 v10, v88, v89
	v_cvt_pk_bf16_f32 v11, v90, v91
	v_cvt_pk_bf16_f32 v12, v92, v93
	v_cvt_pk_bf16_f32 v13, v94, v95
	v_cvt_pk_bf16_f32 v6, v96, v97
	v_cvt_pk_bf16_f32 v7, v98, v99
	v_cvt_pk_bf16_f32 v8, v100, v101
	v_cvt_pk_bf16_f32 v9, v102, v103
	v_cvt_pk_bf16_f32 v2, v104, v105
	v_cvt_pk_bf16_f32 v3, v106, v107
	v_cvt_pk_bf16_f32 v4, v108, v109
	v_cvt_pk_bf16_f32 v5, v110, v111
	s_nop 1
	v_permlane32_swap_b32_e32 v14, v15
	v_permlane32_swap_b32_e32 v144, v146
	v_permlane32_swap_b32_e32 v145, v147
	v_permlane32_swap_b32_e32 v10, v12
	v_permlane32_swap_b32_e32 v11, v13
	v_permlane32_swap_b32_e32 v6, v8
	v_permlane32_swap_b32_e32 v7, v9
	v_permlane32_swap_b32_e32 v2, v4
	v_permlane32_swap_b32_e32 v3, v5
	s_cbranch_vccnz .LBB0_1047
	s_and_saveexec_b64 s[20:21], s[4:5]
	ds_write_b32 v197, v0 offset:128
	s_or_b64 exec, exec, s[20:21]
	s_waitcnt lgkmcnt(0)
	v_add_u32_e32 v201, v189, v191
	ds_read_b128 v[220:223], v201 offset:224
	ds_read_b128 v[224:227], v201 offset:192
	ds_read_b128 v[228:231], v201 offset:160
	ds_read_b128 v[232:235], v201 offset:128
	s_waitcnt lgkmcnt(0)
	v_pk_mul_f32 v[76:77], v[76:77], v[220:221]
	v_pk_mul_f32 v[72:73], v[72:73], v[224:225]
	v_pk_mul_f32 v[68:69], v[68:69], v[228:229]
	v_pk_mul_f32 v[78:79], v[78:79], v[222:223]
	v_pk_mul_f32 v[74:75], v[74:75], v[226:227]
	v_pk_mul_f32 v[70:71], v[70:71], v[230:231]
	v_pk_mul_f32 v[66:67], v[66:67], v[234:235]
	v_pk_mul_f32 v[64:65], v[64:65], v[232:233]
	v_pk_mul_f32 v[60:61], v[60:61], v[220:221]
	v_pk_mul_f32 v[56:57], v[56:57], v[224:225]
	v_pk_mul_f32 v[52:53], v[52:53], v[228:229]
	v_pk_mul_f32 v[62:63], v[62:63], v[222:223]
	v_pk_mul_f32 v[58:59], v[58:59], v[226:227]
	v_pk_mul_f32 v[54:55], v[54:55], v[230:231]
	v_pk_mul_f32 v[50:51], v[50:51], v[234:235]
	v_pk_mul_f32 v[48:49], v[48:49], v[232:233]
	v_pk_mul_f32 v[44:45], v[44:45], v[220:221]
	v_pk_mul_f32 v[40:41], v[40:41], v[224:225]
	v_pk_mul_f32 v[36:37], v[36:37], v[228:229]
	v_pk_mul_f32 v[46:47], v[46:47], v[222:223]
	v_pk_mul_f32 v[42:43], v[42:43], v[226:227]
	v_pk_mul_f32 v[38:39], v[38:39], v[230:231]
	v_pk_mul_f32 v[34:35], v[34:35], v[234:235]
	v_pk_mul_f32 v[32:33], v[32:33], v[232:233]
	v_pk_mul_f32 v[28:29], v[28:29], v[220:221]
	v_pk_mul_f32 v[24:25], v[24:25], v[224:225]
	v_pk_mul_f32 v[20:21], v[20:21], v[228:229]
	v_pk_mul_f32 v[30:31], v[30:31], v[222:223]
	v_pk_mul_f32 v[26:27], v[26:27], v[226:227]
	v_pk_mul_f32 v[22:23], v[22:23], v[230:231]
	v_pk_mul_f32 v[18:19], v[18:19], v[234:235]
	v_pk_mul_f32 v[16:17], v[16:17], v[232:233]

.LBB0_1057:
	s_nop 0
	v_max_f32_e32 v0, v80, v81
	v_max3_f32 v0, v0, v82, v83
	v_max3_f32 v0, v0, v84, v85
	v_max3_f32 v0, v0, v86, v87
	v_max3_f32 v0, v0, v88, v89
	v_max3_f32 v0, v0, v90, v91
	v_max3_f32 v0, v0, v92, v93
	v_max3_f32 v0, v0, v94, v95
	v_max3_f32 v0, v0, v96, v97
	v_max3_f32 v0, v0, v98, v99
	v_max3_f32 v0, v0, v100, v101
	v_max3_f32 v0, v0, v102, v103
	v_max3_f32 v0, v0, v104, v105
	v_max3_f32 v0, v0, v106, v107
	v_max3_f32 v0, v0, v108, v109
	v_max3_f32 v0, v0, v110, v111
	v_mov_b32_e32 v2, v0
	s_nop 1
	v_permlane32_swap_b32_e32 v0, v2
	v_max_f32_e32 v0, v0, v2
	v_sub_f32_e32 v2, v0, v186
	v_cmp_ge_f32_e32 vcc, s86, v2
	s_cmp_eq_u64 vcc, exec
	v_max_f32_e32 v2, v186, v0
	s_cselect_b64 vcc, -1, 0
	v_sub_f32_e32 v0, v186, v2
	v_cndmask_b32_e32 v186, v2, v186, vcc
	v_sub_f32_e32 v2, v80, v186
	v_exp_f32_e32 v80, v2
	v_sub_f32_e32 v2, v96, v186
	v_exp_f32_e32 v96, v2
	v_sub_f32_e32 v2, v81, v186
	v_exp_f32_e32 v81, v2
	v_sub_f32_e32 v2, v97, v186
	v_exp_f32_e32 v97, v2
	v_sub_f32_e32 v2, v82, v186
	v_exp_f32_e32 v82, v2
	v_sub_f32_e32 v2, v98, v186
	v_exp_f32_e32 v98, v2
	v_sub_f32_e32 v2, v83, v186
	v_exp_f32_e32 v83, v2
	v_sub_f32_e32 v2, v99, v186
	v_exp_f32_e32 v99, v2
	v_sub_f32_e32 v2, v84, v186
	v_exp_f32_e32 v84, v2
	v_sub_f32_e32 v2, v100, v186
	v_exp_f32_e32 v100, v2
	v_sub_f32_e32 v2, v85, v186
	v_exp_f32_e32 v85, v2
	v_sub_f32_e32 v2, v101, v186
	v_exp_f32_e32 v101, v2
	v_sub_f32_e32 v2, v86, v186
	v_exp_f32_e32 v86, v2
	v_sub_f32_e32 v2, v102, v186
	v_exp_f32_e32 v102, v2
	v_sub_f32_e32 v2, v87, v186
	v_exp_f32_e32 v87, v2
	v_sub_f32_e32 v2, v103, v186
	v_exp_f32_e32 v103, v2
	v_sub_f32_e32 v2, v88, v186
	v_exp_f32_e32 v88, v2
	v_sub_f32_e32 v2, v104, v186
	v_exp_f32_e32 v104, v2
	v_sub_f32_e32 v2, v89, v186
	v_exp_f32_e32 v89, v2
	v_sub_f32_e32 v2, v105, v186
	v_exp_f32_e32 v105, v2
	v_sub_f32_e32 v2, v90, v186
	v_exp_f32_e32 v90, v2
	v_sub_f32_e32 v2, v106, v186
	v_exp_f32_e32 v106, v2
	v_sub_f32_e32 v2, v91, v186
	v_exp_f32_e32 v91, v2
	v_sub_f32_e32 v2, v107, v186
	v_exp_f32_e32 v107, v2
	v_sub_f32_e32 v2, v92, v186
	v_exp_f32_e32 v92, v2
	v_sub_f32_e32 v2, v108, v186
	v_exp_f32_e32 v108, v2
	v_sub_f32_e32 v2, v93, v186
	v_exp_f32_e32 v93, v2
	v_sub_f32_e32 v2, v109, v186
	v_exp_f32_e32 v109, v2
	v_sub_f32_e32 v2, v94, v186
	v_exp_f32_e32 v94, v2
	v_sub_f32_e32 v2, v110, v186
	v_exp_f32_e32 v110, v2
	v_sub_f32_e32 v2, v95, v186
	v_exp_f32_e32 v95, v2
	v_sub_f32_e32 v2, v111, v186
	v_exp_f32_e32 v111, v2
	v_add_f32_e32 v2, v80, v96
	v_add_f32_e32 v2, 0, v2
	v_add_f32_e32 v3, v81, v97
	v_add_f32_e32 v2, v3, v2
	v_add_f32_e32 v3, v82, v98
	v_add_f32_e32 v2, v3, v2
	v_add_f32_e32 v3, v83, v99
	v_add_f32_e32 v2, v3, v2
	v_add_f32_e32 v3, v84, v100
	v_add_f32_e32 v2, v3, v2
	v_add_f32_e32 v3, v85, v101
	v_add_f32_e32 v2, v3, v2
	v_add_f32_e32 v3, v86, v102
	v_add_f32_e32 v2, v3, v2
	v_add_f32_e32 v3, v87, v103
	v_add_f32_e32 v2, v3, v2
	v_add_f32_e32 v3, v88, v104
	v_add_f32_e32 v2, v3, v2
	v_add_f32_e32 v3, v89, v105
	v_add_f32_e32 v2, v3, v2
	v_add_f32_e32 v3, v90, v106
	v_add_f32_e32 v2, v3, v2
	v_add_f32_e32 v3, v91, v107
	v_add_f32_e32 v2, v3, v2
	v_add_f32_e32 v3, v92, v108
	v_add_f32_e32 v2, v3, v2
	v_add_f32_e32 v3, v93, v109
	v_add_f32_e32 v2, v3, v2
	v_add_f32_e32 v3, v94, v110
	v_exp_f32_e32 v0, v0
	v_add_f32_e32 v2, v3, v2
	v_add_f32_e32 v3, v95, v111
	v_add_f32_e32 v14, v3, v2
	v_mov_b32_e32 v15, v14
	v_cvt_pk_bf16_f32 v144, v80, v81
	v_cvt_pk_bf16_f32 v145, v82, v83
	v_cvt_pk_bf16_f32 v146, v84, v85
	v_cvt_pk_bf16_f32 v147, v86, v87
	v_cvt_pk_bf16_f32 v10, v88, v89
	v_cvt_pk_bf16_f32 v11, v90, v91
	v_cvt_pk_bf16_f32 v12, v92, v93
	v_cvt_pk_bf16_f32 v13, v94, v95
	v_cvt_pk_bf16_f32 v6, v96, v97
	v_cvt_pk_bf16_f32 v7, v98, v99
	v_cvt_pk_bf16_f32 v8, v100, v101
	v_cvt_pk_bf16_f32 v9, v102, v103
	v_cvt_pk_bf16_f32 v2, v104, v105
	v_cvt_pk_bf16_f32 v3, v106, v107
	v_cvt_pk_bf16_f32 v4, v108, v109
	v_cvt_pk_bf16_f32 v5, v110, v111
	s_nop 1
	v_permlane32_swap_b32_e32 v14, v15
	v_permlane32_swap_b32_e32 v144, v146
	v_permlane32_swap_b32_e32 v145, v147
	v_permlane32_swap_b32_e32 v10, v12
	v_permlane32_swap_b32_e32 v11, v13
	v_permlane32_swap_b32_e32 v6, v8
	v_permlane32_swap_b32_e32 v7, v9
	v_permlane32_swap_b32_e32 v2, v4
	v_permlane32_swap_b32_e32 v3, v5
	s_cbranch_vccnz .LBB0_1061
	s_and_saveexec_b64 s[26:27], s[4:5]
	ds_write_b32 v197, v0 offset:128
	s_or_b64 exec, exec, s[26:27]
	s_waitcnt lgkmcnt(0)
	v_add_u32_e32 v201, v189, v191
	ds_read_b128 v[206:209], v201 offset:224
	ds_read_b128 v[220:223], v201 offset:192
	ds_read_b128 v[224:227], v201 offset:160
	ds_read_b128 v[228:231], v201 offset:128
	s_waitcnt lgkmcnt(0)
	v_pk_mul_f32 v[76:77], v[76:77], v[206:207]
	v_pk_mul_f32 v[72:73], v[72:73], v[220:221]
	v_pk_mul_f32 v[68:69], v[68:69], v[224:225]
	v_pk_mul_f32 v[78:79], v[78:79], v[208:209]
	v_pk_mul_f32 v[74:75], v[74:75], v[222:223]
	v_pk_mul_f32 v[70:71], v[70:71], v[226:227]
	v_pk_mul_f32 v[66:67], v[66:67], v[230:231]
	v_pk_mul_f32 v[64:65], v[64:65], v[228:229]
	v_pk_mul_f32 v[60:61], v[60:61], v[206:207]
	v_pk_mul_f32 v[56:57], v[56:57], v[220:221]
	v_pk_mul_f32 v[52:53], v[52:53], v[224:225]
	v_pk_mul_f32 v[62:63], v[62:63], v[208:209]
	v_pk_mul_f32 v[58:59], v[58:59], v[222:223]
	v_pk_mul_f32 v[54:55], v[54:55], v[226:227]
	v_pk_mul_f32 v[50:51], v[50:51], v[230:231]
	v_pk_mul_f32 v[48:49], v[48:49], v[228:229]
	v_pk_mul_f32 v[44:45], v[44:45], v[206:207]
	v_pk_mul_f32 v[40:41], v[40:41], v[220:221]
	v_pk_mul_f32 v[36:37], v[36:37], v[224:225]
	v_pk_mul_f32 v[46:47], v[46:47], v[208:209]
	v_pk_mul_f32 v[42:43], v[42:43], v[222:223]
	v_pk_mul_f32 v[38:39], v[38:39], v[226:227]
	v_pk_mul_f32 v[34:35], v[34:35], v[230:231]
	v_pk_mul_f32 v[32:33], v[32:33], v[228:229]
	v_pk_mul_f32 v[28:29], v[28:29], v[206:207]
	v_pk_mul_f32 v[24:25], v[24:25], v[220:221]
	v_pk_mul_f32 v[20:21], v[20:21], v[224:225]
	v_pk_mul_f32 v[30:31], v[30:31], v[208:209]
	v_pk_mul_f32 v[26:27], v[26:27], v[222:223]
	v_pk_mul_f32 v[22:23], v[22:23], v[226:227]
	v_pk_mul_f32 v[18:19], v[18:19], v[230:231]
	v_pk_mul_f32 v[16:17], v[16:17], v[228:229]

.LBB0_1078:
	v_max_f32_e32 v0, v80, v81
	v_max3_f32 v0, v0, v82, v83
	v_max3_f32 v0, v0, v84, v85
	v_max3_f32 v0, v0, v86, v87
	v_max3_f32 v0, v0, v88, v89
	v_max3_f32 v0, v0, v90, v91
	v_max3_f32 v0, v0, v92, v93
	v_max3_f32 v0, v0, v94, v95
	v_max3_f32 v0, v0, v96, v97
	v_max3_f32 v0, v0, v98, v99
	v_max3_f32 v0, v0, v100, v101
	v_max3_f32 v0, v0, v102, v103
	v_max3_f32 v0, v0, v104, v105
	v_max3_f32 v0, v0, v106, v107
	v_max3_f32 v0, v0, v108, v109
	v_max3_f32 v0, v0, v110, v111
	v_mov_b32_e32 v2, v0
	s_nop 1
	v_permlane32_swap_b32_e32 v0, v2
	v_max_f32_e32 v0, v0, v2
	v_sub_f32_e32 v2, v0, v177
	v_cmp_ge_f32_e32 vcc, s86, v2
	s_cmp_eq_u64 vcc, exec
	v_max_f32_e32 v2, v177, v0
	s_cselect_b64 vcc, -1, 0
	v_sub_f32_e32 v0, v177, v2
	v_cndmask_b32_e32 v177, v2, v177, vcc
	v_sub_f32_e32 v2, v80, v177
	v_exp_f32_e32 v80, v2
	v_sub_f32_e32 v2, v96, v177
	v_exp_f32_e32 v96, v2
	v_sub_f32_e32 v2, v81, v177
	v_exp_f32_e32 v81, v2
	v_sub_f32_e32 v2, v97, v177
	v_exp_f32_e32 v97, v2
	v_sub_f32_e32 v2, v82, v177
	v_exp_f32_e32 v82, v2
	v_sub_f32_e32 v2, v98, v177
	v_exp_f32_e32 v98, v2
	v_sub_f32_e32 v2, v83, v177
	v_exp_f32_e32 v83, v2
	v_sub_f32_e32 v2, v99, v177
	v_exp_f32_e32 v99, v2
	v_sub_f32_e32 v2, v84, v177
	v_exp_f32_e32 v84, v2
	v_sub_f32_e32 v2, v100, v177
	v_exp_f32_e32 v100, v2
	v_sub_f32_e32 v2, v85, v177
	v_exp_f32_e32 v85, v2
	v_sub_f32_e32 v2, v101, v177
	v_exp_f32_e32 v101, v2
	v_sub_f32_e32 v2, v86, v177
	v_exp_f32_e32 v86, v2
	v_sub_f32_e32 v2, v102, v177
	v_exp_f32_e32 v102, v2
	v_sub_f32_e32 v2, v87, v177
	v_exp_f32_e32 v87, v2
	v_sub_f32_e32 v2, v103, v177
	v_exp_f32_e32 v103, v2
	v_sub_f32_e32 v2, v88, v177
	v_exp_f32_e32 v88, v2
	v_sub_f32_e32 v2, v104, v177
	v_exp_f32_e32 v104, v2
	v_sub_f32_e32 v2, v89, v177
	v_exp_f32_e32 v89, v2
	v_sub_f32_e32 v2, v105, v177
	v_exp_f32_e32 v105, v2
	v_sub_f32_e32 v2, v90, v177
	v_exp_f32_e32 v90, v2
	v_sub_f32_e32 v2, v106, v177
	v_exp_f32_e32 v106, v2
	v_sub_f32_e32 v2, v91, v177
	v_exp_f32_e32 v91, v2
	v_sub_f32_e32 v2, v107, v177
	v_exp_f32_e32 v107, v2
	v_sub_f32_e32 v2, v92, v177
	v_exp_f32_e32 v92, v2
	v_sub_f32_e32 v2, v108, v177
	v_exp_f32_e32 v108, v2
	v_sub_f32_e32 v2, v93, v177
	v_exp_f32_e32 v93, v2
	v_sub_f32_e32 v2, v109, v177
	v_exp_f32_e32 v109, v2
	v_sub_f32_e32 v2, v94, v177
	v_exp_f32_e32 v94, v2
	v_sub_f32_e32 v2, v110, v177
	v_exp_f32_e32 v110, v2
	v_sub_f32_e32 v2, v95, v177
	v_exp_f32_e32 v95, v2
	v_sub_f32_e32 v2, v111, v177
	v_exp_f32_e32 v111, v2
	v_add_f32_e32 v2, v80, v96
	v_add_f32_e32 v2, 0, v2
	v_add_f32_e32 v3, v81, v97
	v_add_f32_e32 v2, v3, v2
	v_add_f32_e32 v3, v82, v98
	v_add_f32_e32 v2, v3, v2
	v_add_f32_e32 v3, v83, v99
	v_add_f32_e32 v2, v3, v2
	v_add_f32_e32 v3, v84, v100
	v_add_f32_e32 v2, v3, v2
	v_add_f32_e32 v3, v85, v101
	v_add_f32_e32 v2, v3, v2
	v_add_f32_e32 v3, v86, v102
	v_add_f32_e32 v2, v3, v2
	v_add_f32_e32 v3, v87, v103
	v_add_f32_e32 v2, v3, v2
	v_add_f32_e32 v3, v88, v104
	v_add_f32_e32 v2, v3, v2
	v_add_f32_e32 v3, v89, v105
	v_add_f32_e32 v2, v3, v2
	v_add_f32_e32 v3, v90, v106
	v_add_f32_e32 v2, v3, v2
	v_add_f32_e32 v3, v91, v107
	v_add_f32_e32 v2, v3, v2
	v_add_f32_e32 v3, v92, v108
	v_add_f32_e32 v2, v3, v2
	v_add_f32_e32 v3, v93, v109
	v_add_f32_e32 v2, v3, v2
	v_add_f32_e32 v3, v94, v110
	v_exp_f32_e32 v0, v0
	v_add_f32_e32 v2, v3, v2
	v_add_f32_e32 v3, v95, v111
	v_add_f32_e32 v180, v3, v2
	v_mov_b32_e32 v181, v180
	v_cvt_pk_bf16_f32 v148, v80, v81
	v_cvt_pk_bf16_f32 v149, v82, v83
	v_cvt_pk_bf16_f32 v150, v84, v85
	v_cvt_pk_bf16_f32 v151, v86, v87
	v_cvt_pk_bf16_f32 v10, v88, v89
	v_cvt_pk_bf16_f32 v11, v90, v91
	v_cvt_pk_bf16_f32 v12, v92, v93
	v_cvt_pk_bf16_f32 v13, v94, v95
	v_cvt_pk_bf16_f32 v6, v96, v97
	v_cvt_pk_bf16_f32 v7, v98, v99
	v_cvt_pk_bf16_f32 v8, v100, v101
	v_cvt_pk_bf16_f32 v9, v102, v103
	v_cvt_pk_bf16_f32 v2, v104, v105
	v_cvt_pk_bf16_f32 v3, v106, v107
	v_cvt_pk_bf16_f32 v4, v108, v109
	v_cvt_pk_bf16_f32 v5, v110, v111
	s_nop 1
	v_permlane32_swap_b32_e32 v180, v181
	v_permlane32_swap_b32_e32 v148, v150
	v_permlane32_swap_b32_e32 v149, v151
	v_permlane32_swap_b32_e32 v10, v12
	v_permlane32_swap_b32_e32 v11, v13
	v_permlane32_swap_b32_e32 v6, v8
	v_permlane32_swap_b32_e32 v7, v9
	v_permlane32_swap_b32_e32 v2, v4
	v_permlane32_swap_b32_e32 v3, v5
	s_cbranch_vccnz .LBB0_1082
	s_and_saveexec_b64 s[24:25], s[0:1]
	ds_write_b32 v173, v0 offset:128
	s_or_b64 exec, exec, s[24:25]
	s_waitcnt lgkmcnt(0)
	v_add_u32_e32 v194, v165, v167
	ds_read_b128 v[182:185], v194 offset:224
	ds_read_b128 v[186:189], v194 offset:192
	ds_read_b128 v[190:193], v194 offset:160
	ds_read_b128 v[194:197], v194 offset:128
	s_waitcnt lgkmcnt(0)
	v_pk_mul_f32 v[76:77], v[76:77], v[182:183]
	v_pk_mul_f32 v[72:73], v[72:73], v[186:187]
	v_pk_mul_f32 v[68:69], v[68:69], v[190:191]
	v_pk_mul_f32 v[78:79], v[78:79], v[184:185]
	v_pk_mul_f32 v[74:75], v[74:75], v[188:189]
	v_pk_mul_f32 v[70:71], v[70:71], v[192:193]
	v_pk_mul_f32 v[66:67], v[66:67], v[196:197]
	v_pk_mul_f32 v[64:65], v[64:65], v[194:195]
	v_pk_mul_f32 v[60:61], v[60:61], v[182:183]
	v_pk_mul_f32 v[56:57], v[56:57], v[186:187]
	v_pk_mul_f32 v[52:53], v[52:53], v[190:191]
	v_pk_mul_f32 v[62:63], v[62:63], v[184:185]
	v_pk_mul_f32 v[58:59], v[58:59], v[188:189]
	v_pk_mul_f32 v[54:55], v[54:55], v[192:193]
	v_pk_mul_f32 v[50:51], v[50:51], v[196:197]
	v_pk_mul_f32 v[48:49], v[48:49], v[194:195]
	v_pk_mul_f32 v[44:45], v[44:45], v[182:183]
	v_pk_mul_f32 v[40:41], v[40:41], v[186:187]
	v_pk_mul_f32 v[36:37], v[36:37], v[190:191]
	v_pk_mul_f32 v[46:47], v[46:47], v[184:185]
	v_pk_mul_f32 v[42:43], v[42:43], v[188:189]
	v_pk_mul_f32 v[38:39], v[38:39], v[192:193]
	v_pk_mul_f32 v[34:35], v[34:35], v[196:197]
	v_pk_mul_f32 v[32:33], v[32:33], v[194:195]
	v_pk_mul_f32 v[28:29], v[28:29], v[182:183]
	v_pk_mul_f32 v[24:25], v[24:25], v[186:187]
	v_pk_mul_f32 v[20:21], v[20:21], v[190:191]
	v_pk_mul_f32 v[30:31], v[30:31], v[184:185]
	v_pk_mul_f32 v[26:27], v[26:27], v[188:189]
	v_pk_mul_f32 v[22:23], v[22:23], v[192:193]
	v_pk_mul_f32 v[18:19], v[18:19], v[196:197]
	v_pk_mul_f32 v[16:17], v[16:17], v[194:195]

.LBB0_1088:
	v_max_f32_e32 v0, v80, v81
	v_max3_f32 v0, v0, v82, v83
	v_max3_f32 v0, v0, v84, v85
	v_max3_f32 v0, v0, v86, v87
	v_max3_f32 v0, v0, v88, v89
	v_max3_f32 v0, v0, v90, v91
	v_max3_f32 v0, v0, v92, v93
	v_max3_f32 v0, v0, v94, v95
	v_max3_f32 v0, v0, v96, v97
	v_max3_f32 v0, v0, v98, v99
	v_max3_f32 v0, v0, v100, v101
	v_max3_f32 v0, v0, v102, v103
	v_max3_f32 v0, v0, v104, v105
	v_max3_f32 v0, v0, v106, v107
	v_max3_f32 v0, v0, v108, v109
	v_max3_f32 v0, v0, v110, v111
	v_mov_b32_e32 v2, v0
	s_nop 1
	v_permlane32_swap_b32_e32 v0, v2
	v_max_f32_e32 v0, v0, v2
	v_sub_f32_e32 v2, v0, v177
	v_cmp_ge_f32_e32 vcc, s86, v2
	s_cmp_eq_u64 vcc, exec
	v_max_f32_e32 v2, v177, v0
	s_cselect_b64 vcc, -1, 0
	v_sub_f32_e32 v0, v177, v2
	v_cndmask_b32_e32 v177, v2, v177, vcc
	v_sub_f32_e32 v2, v80, v177
	v_exp_f32_e32 v80, v2
	v_sub_f32_e32 v2, v96, v177
	v_exp_f32_e32 v96, v2
	v_sub_f32_e32 v2, v81, v177
	v_exp_f32_e32 v81, v2
	v_sub_f32_e32 v2, v97, v177
	v_exp_f32_e32 v97, v2
	v_sub_f32_e32 v2, v82, v177
	v_exp_f32_e32 v82, v2
	v_sub_f32_e32 v2, v98, v177
	v_exp_f32_e32 v98, v2
	v_sub_f32_e32 v2, v83, v177
	v_exp_f32_e32 v83, v2
	v_sub_f32_e32 v2, v99, v177
	v_exp_f32_e32 v99, v2
	v_sub_f32_e32 v2, v84, v177
	v_exp_f32_e32 v84, v2
	v_sub_f32_e32 v2, v100, v177
	v_exp_f32_e32 v100, v2
	v_sub_f32_e32 v2, v85, v177
	v_exp_f32_e32 v85, v2
	v_sub_f32_e32 v2, v101, v177
	v_exp_f32_e32 v101, v2
	v_sub_f32_e32 v2, v86, v177
	v_exp_f32_e32 v86, v2
	v_sub_f32_e32 v2, v102, v177
	v_exp_f32_e32 v102, v2
	v_sub_f32_e32 v2, v87, v177
	v_exp_f32_e32 v87, v2
	v_sub_f32_e32 v2, v103, v177
	v_exp_f32_e32 v103, v2
	v_sub_f32_e32 v2, v88, v177
	v_exp_f32_e32 v88, v2
	v_sub_f32_e32 v2, v104, v177
	v_exp_f32_e32 v104, v2
	v_sub_f32_e32 v2, v89, v177
	v_exp_f32_e32 v89, v2
	v_sub_f32_e32 v2, v105, v177
	v_exp_f32_e32 v105, v2
	v_sub_f32_e32 v2, v90, v177
	v_exp_f32_e32 v90, v2
	v_sub_f32_e32 v2, v106, v177
	v_exp_f32_e32 v106, v2
	v_sub_f32_e32 v2, v91, v177
	v_exp_f32_e32 v91, v2
	v_sub_f32_e32 v2, v107, v177
	v_exp_f32_e32 v107, v2
	v_sub_f32_e32 v2, v92, v177
	v_exp_f32_e32 v92, v2
	v_sub_f32_e32 v2, v108, v177
	v_exp_f32_e32 v108, v2
	v_sub_f32_e32 v2, v93, v177
	v_exp_f32_e32 v93, v2
	v_sub_f32_e32 v2, v109, v177
	v_exp_f32_e32 v109, v2
	v_sub_f32_e32 v2, v94, v177
	v_exp_f32_e32 v94, v2
	v_sub_f32_e32 v2, v110, v177
	v_exp_f32_e32 v110, v2
	v_sub_f32_e32 v2, v95, v177
	v_exp_f32_e32 v95, v2
	v_sub_f32_e32 v2, v111, v177
	v_exp_f32_e32 v111, v2
	v_add_f32_e32 v2, v80, v96
	v_add_f32_e32 v2, 0, v2
	v_add_f32_e32 v3, v81, v97
	v_add_f32_e32 v2, v3, v2
	v_add_f32_e32 v3, v82, v98
	v_add_f32_e32 v2, v3, v2
	v_add_f32_e32 v3, v83, v99
	v_add_f32_e32 v2, v3, v2
	v_add_f32_e32 v3, v84, v100
	v_add_f32_e32 v2, v3, v2
	v_add_f32_e32 v3, v85, v101
	v_add_f32_e32 v2, v3, v2
	v_add_f32_e32 v3, v86, v102
	v_add_f32_e32 v2, v3, v2
	v_add_f32_e32 v3, v87, v103
	v_add_f32_e32 v2, v3, v2
	v_add_f32_e32 v3, v88, v104
	v_add_f32_e32 v2, v3, v2
	v_add_f32_e32 v3, v89, v105
	v_add_f32_e32 v2, v3, v2
	v_add_f32_e32 v3, v90, v106
	v_add_f32_e32 v2, v3, v2
	v_add_f32_e32 v3, v91, v107
	v_add_f32_e32 v2, v3, v2
	v_add_f32_e32 v3, v92, v108
	v_add_f32_e32 v2, v3, v2
	v_add_f32_e32 v3, v93, v109
	v_add_f32_e32 v2, v3, v2
	v_add_f32_e32 v3, v94, v110
	v_exp_f32_e32 v0, v0
	v_add_f32_e32 v2, v3, v2
	v_add_f32_e32 v3, v95, v111
	v_add_f32_e32 v144, v3, v2
	v_mov_b32_e32 v145, v144
	v_cvt_pk_bf16_f32 v148, v80, v81
	v_cvt_pk_bf16_f32 v149, v82, v83
	v_cvt_pk_bf16_f32 v150, v84, v85
	v_cvt_pk_bf16_f32 v151, v86, v87
	v_cvt_pk_bf16_f32 v10, v88, v89
	v_cvt_pk_bf16_f32 v11, v90, v91
	v_cvt_pk_bf16_f32 v12, v92, v93
	v_cvt_pk_bf16_f32 v13, v94, v95
	v_cvt_pk_bf16_f32 v6, v96, v97
	v_cvt_pk_bf16_f32 v7, v98, v99
	v_cvt_pk_bf16_f32 v8, v100, v101
	v_cvt_pk_bf16_f32 v9, v102, v103
	v_cvt_pk_bf16_f32 v2, v104, v105
	v_cvt_pk_bf16_f32 v3, v106, v107
	v_cvt_pk_bf16_f32 v4, v108, v109
	v_cvt_pk_bf16_f32 v5, v110, v111
	s_nop 1
	v_permlane32_swap_b32_e32 v144, v145
	v_permlane32_swap_b32_e32 v148, v150
	v_permlane32_swap_b32_e32 v149, v151
	v_permlane32_swap_b32_e32 v10, v12
	v_permlane32_swap_b32_e32 v11, v13
	v_permlane32_swap_b32_e32 v6, v8
	v_permlane32_swap_b32_e32 v7, v9
	v_permlane32_swap_b32_e32 v2, v4
	v_permlane32_swap_b32_e32 v3, v5
	s_cbranch_vccnz .LBB0_1092
	s_and_saveexec_b64 s[26:27], s[0:1]
	ds_write_b32 v173, v0 offset:128
	s_or_b64 exec, exec, s[26:27]
	s_waitcnt lgkmcnt(0)
	v_add_u32_e32 v192, v165, v167
	ds_read_b128 v[180:183], v192 offset:224
	ds_read_b128 v[184:187], v192 offset:192
	ds_read_b128 v[188:191], v192 offset:160
	ds_read_b128 v[192:195], v192 offset:128
	s_waitcnt lgkmcnt(0)
	v_pk_mul_f32 v[76:77], v[76:77], v[180:181]
	v_pk_mul_f32 v[72:73], v[72:73], v[184:185]
	v_pk_mul_f32 v[68:69], v[68:69], v[188:189]
	v_pk_mul_f32 v[78:79], v[78:79], v[182:183]
	v_pk_mul_f32 v[74:75], v[74:75], v[186:187]
	v_pk_mul_f32 v[70:71], v[70:71], v[190:191]
	v_pk_mul_f32 v[66:67], v[66:67], v[194:195]
	v_pk_mul_f32 v[64:65], v[64:65], v[192:193]
	v_pk_mul_f32 v[60:61], v[60:61], v[180:181]
	v_pk_mul_f32 v[56:57], v[56:57], v[184:185]
	v_pk_mul_f32 v[52:53], v[52:53], v[188:189]
	v_pk_mul_f32 v[62:63], v[62:63], v[182:183]
	v_pk_mul_f32 v[58:59], v[58:59], v[186:187]
	v_pk_mul_f32 v[54:55], v[54:55], v[190:191]
	v_pk_mul_f32 v[50:51], v[50:51], v[194:195]
	v_pk_mul_f32 v[48:49], v[48:49], v[192:193]
	v_pk_mul_f32 v[44:45], v[44:45], v[180:181]
	v_pk_mul_f32 v[40:41], v[40:41], v[184:185]
	v_pk_mul_f32 v[36:37], v[36:37], v[188:189]
	v_pk_mul_f32 v[46:47], v[46:47], v[182:183]
	v_pk_mul_f32 v[42:43], v[42:43], v[186:187]
	v_pk_mul_f32 v[38:39], v[38:39], v[190:191]
	v_pk_mul_f32 v[34:35], v[34:35], v[194:195]
	v_pk_mul_f32 v[32:33], v[32:33], v[192:193]
	v_pk_mul_f32 v[28:29], v[28:29], v[180:181]
	v_pk_mul_f32 v[24:25], v[24:25], v[184:185]
	v_pk_mul_f32 v[20:21], v[20:21], v[188:189]
	v_pk_mul_f32 v[30:31], v[30:31], v[182:183]
	v_pk_mul_f32 v[26:27], v[26:27], v[186:187]
	v_pk_mul_f32 v[22:23], v[22:23], v[190:191]
	v_pk_mul_f32 v[18:19], v[18:19], v[194:195]
	v_pk_mul_f32 v[16:17], v[16:17], v[192:193]

.LBB0_1132:
	s_and_b64 s[44:45], s[36:37], s[40:41]
	s_and_saveexec_b64 s[20:21], s[44:45]
	s_cbranch_execz .LBB0_1138
	v_max_f32_e32 v0, v80, v81
	v_max3_f32 v0, v0, v82, v83
	v_max3_f32 v0, v0, v84, v85
	v_max3_f32 v0, v0, v86, v87
	v_max3_f32 v0, v0, v88, v89
	v_max3_f32 v0, v0, v90, v91
	v_max3_f32 v0, v0, v92, v93
	v_max3_f32 v0, v0, v94, v95
	v_max3_f32 v0, v0, v96, v97
	v_max3_f32 v0, v0, v98, v99
	v_max3_f32 v0, v0, v100, v101
	v_max3_f32 v0, v0, v102, v103
	v_max3_f32 v0, v0, v104, v105
	v_max3_f32 v0, v0, v106, v107
	v_max3_f32 v0, v0, v108, v109
	v_max3_f32 v0, v0, v110, v111
	v_mov_b32_e32 v2, v0
	s_nop 1
	v_permlane32_swap_b32_e32 v0, v2
	v_max_f32_e32 v0, v0, v2
	v_sub_f32_e32 v2, v0, v173
	v_cmp_ge_f32_e32 vcc, s86, v2
	s_cmp_eq_u64 vcc, exec
	v_max_f32_e32 v2, v173, v0
	s_cselect_b64 vcc, -1, 0
	v_sub_f32_e32 v0, v173, v2
	v_cndmask_b32_e32 v173, v2, v173, vcc
	v_sub_f32_e32 v2, v80, v173
	v_exp_f32_e32 v80, v2
	v_sub_f32_e32 v2, v96, v173
	v_exp_f32_e32 v96, v2
	v_sub_f32_e32 v2, v81, v173
	v_exp_f32_e32 v81, v2
	v_sub_f32_e32 v2, v97, v173
	v_exp_f32_e32 v97, v2
	v_sub_f32_e32 v2, v82, v173
	v_exp_f32_e32 v82, v2
	v_sub_f32_e32 v2, v98, v173
	v_exp_f32_e32 v98, v2
	v_sub_f32_e32 v2, v83, v173
	v_exp_f32_e32 v83, v2
	v_sub_f32_e32 v2, v99, v173
	v_exp_f32_e32 v99, v2
	v_sub_f32_e32 v2, v84, v173
	v_exp_f32_e32 v84, v2
	v_sub_f32_e32 v2, v100, v173
	v_exp_f32_e32 v100, v2
	v_sub_f32_e32 v2, v85, v173
	v_exp_f32_e32 v85, v2
	v_sub_f32_e32 v2, v101, v173
	v_exp_f32_e32 v101, v2
	v_sub_f32_e32 v2, v86, v173
	v_exp_f32_e32 v86, v2
	v_sub_f32_e32 v2, v102, v173
	v_exp_f32_e32 v102, v2
	v_sub_f32_e32 v2, v87, v173
	v_exp_f32_e32 v87, v2
	v_sub_f32_e32 v2, v103, v173
	v_exp_f32_e32 v103, v2
	v_sub_f32_e32 v2, v88, v173
	v_exp_f32_e32 v88, v2
	v_sub_f32_e32 v2, v104, v173
	v_exp_f32_e32 v104, v2
	v_sub_f32_e32 v2, v89, v173
	v_exp_f32_e32 v89, v2
	v_sub_f32_e32 v2, v105, v173
	v_exp_f32_e32 v105, v2
	v_sub_f32_e32 v2, v90, v173
	v_exp_f32_e32 v90, v2
	v_sub_f32_e32 v2, v106, v173
	v_exp_f32_e32 v106, v2
	v_sub_f32_e32 v2, v91, v173
	v_exp_f32_e32 v91, v2
	v_sub_f32_e32 v2, v107, v173
	v_exp_f32_e32 v107, v2
	v_sub_f32_e32 v2, v92, v173
	v_exp_f32_e32 v92, v2
	v_sub_f32_e32 v2, v108, v173
	v_exp_f32_e32 v108, v2
	v_sub_f32_e32 v2, v93, v173
	v_exp_f32_e32 v93, v2
	v_sub_f32_e32 v2, v109, v173
	v_exp_f32_e32 v109, v2
	v_sub_f32_e32 v2, v94, v173
	v_exp_f32_e32 v94, v2
	v_sub_f32_e32 v2, v110, v173
	v_exp_f32_e32 v110, v2
	v_sub_f32_e32 v2, v95, v173
	v_exp_f32_e32 v95, v2
	v_sub_f32_e32 v2, v111, v173
	v_exp_f32_e32 v111, v2
	v_add_f32_e32 v2, v80, v96
	v_add_f32_e32 v2, 0, v2
	v_add_f32_e32 v3, v81, v97
	v_add_f32_e32 v2, v3, v2
	v_add_f32_e32 v3, v82, v98
	v_add_f32_e32 v2, v3, v2
	v_add_f32_e32 v3, v83, v99
	v_add_f32_e32 v2, v3, v2
	v_add_f32_e32 v3, v84, v100
	v_add_f32_e32 v2, v3, v2
	v_add_f32_e32 v3, v85, v101
	v_add_f32_e32 v2, v3, v2
	v_add_f32_e32 v3, v86, v102
	v_add_f32_e32 v2, v3, v2
	v_add_f32_e32 v3, v87, v103
	v_add_f32_e32 v2, v3, v2
	v_add_f32_e32 v3, v88, v104
	v_add_f32_e32 v2, v3, v2
	v_add_f32_e32 v3, v89, v105
	v_add_f32_e32 v2, v3, v2
	v_add_f32_e32 v3, v90, v106
	v_add_f32_e32 v2, v3, v2
	v_add_f32_e32 v3, v91, v107
	v_add_f32_e32 v2, v3, v2
	v_add_f32_e32 v3, v92, v108
	v_add_f32_e32 v2, v3, v2
	v_add_f32_e32 v3, v93, v109
	v_add_f32_e32 v2, v3, v2
	v_add_f32_e32 v3, v94, v110
	v_exp_f32_e32 v0, v0
	v_add_f32_e32 v2, v3, v2
	v_add_f32_e32 v3, v95, v111
	v_add_f32_e32 v14, v3, v2
	v_mov_b32_e32 v15, v14
	v_cvt_pk_bf16_f32 v144, v80, v81
	v_cvt_pk_bf16_f32 v145, v82, v83
	v_cvt_pk_bf16_f32 v146, v84, v85
	v_cvt_pk_bf16_f32 v147, v86, v87
	v_cvt_pk_bf16_f32 v10, v88, v89
	v_cvt_pk_bf16_f32 v11, v90, v91
	v_cvt_pk_bf16_f32 v12, v92, v93
	v_cvt_pk_bf16_f32 v13, v94, v95
	v_cvt_pk_bf16_f32 v6, v96, v97
	v_cvt_pk_bf16_f32 v7, v98, v99
	v_cvt_pk_bf16_f32 v8, v100, v101
	v_cvt_pk_bf16_f32 v9, v102, v103
	v_cvt_pk_bf16_f32 v2, v104, v105
	v_cvt_pk_bf16_f32 v3, v106, v107
	v_cvt_pk_bf16_f32 v4, v108, v109
	v_cvt_pk_bf16_f32 v5, v110, v111
	s_nop 1
	v_permlane32_swap_b32_e32 v14, v15
	v_permlane32_swap_b32_e32 v144, v146
	v_permlane32_swap_b32_e32 v145, v147
	v_permlane32_swap_b32_e32 v10, v12
	v_permlane32_swap_b32_e32 v11, v13
	v_permlane32_swap_b32_e32 v6, v8
	v_permlane32_swap_b32_e32 v7, v9
	v_permlane32_swap_b32_e32 v2, v4
	v_permlane32_swap_b32_e32 v3, v5
	s_cbranch_vccnz .LBB0_1137
	s_and_saveexec_b64 s[44:45], s[16:17]
	ds_write_b32 v168, v0 offset:128
	s_or_b64 exec, exec, s[44:45]
	s_waitcnt lgkmcnt(0)
	v_add_u32_e32 v183, v166, v167
	ds_read_b128 v[184:187], v183 offset:224
	ds_read_b128 v[188:191], v183 offset:192
	ds_read_b128 v[192:195], v183 offset:160
	ds_read_b128 v[216:219], v183 offset:128
	s_waitcnt lgkmcnt(0)
	v_pk_mul_f32 v[76:77], v[76:77], v[184:185]
	v_pk_mul_f32 v[72:73], v[72:73], v[188:189]
	v_pk_mul_f32 v[68:69], v[68:69], v[192:193]
	v_pk_mul_f32 v[78:79], v[78:79], v[186:187]
	v_pk_mul_f32 v[74:75], v[74:75], v[190:191]
	v_pk_mul_f32 v[70:71], v[70:71], v[194:195]
	v_pk_mul_f32 v[66:67], v[66:67], v[218:219]
	v_pk_mul_f32 v[64:65], v[64:65], v[216:217]
	v_pk_mul_f32 v[60:61], v[60:61], v[184:185]
	v_pk_mul_f32 v[56:57], v[56:57], v[188:189]
	v_pk_mul_f32 v[52:53], v[52:53], v[192:193]
	v_pk_mul_f32 v[62:63], v[62:63], v[186:187]
	v_pk_mul_f32 v[58:59], v[58:59], v[190:191]
	v_pk_mul_f32 v[54:55], v[54:55], v[194:195]
	v_pk_mul_f32 v[50:51], v[50:51], v[218:219]
	v_pk_mul_f32 v[48:49], v[48:49], v[216:217]
	v_pk_mul_f32 v[44:45], v[44:45], v[184:185]
	v_pk_mul_f32 v[40:41], v[40:41], v[188:189]
	v_pk_mul_f32 v[36:37], v[36:37], v[192:193]
	v_pk_mul_f32 v[46:47], v[46:47], v[186:187]
	v_pk_mul_f32 v[42:43], v[42:43], v[190:191]
	v_pk_mul_f32 v[38:39], v[38:39], v[194:195]
	v_pk_mul_f32 v[34:35], v[34:35], v[218:219]
	v_pk_mul_f32 v[32:33], v[32:33], v[216:217]
	v_pk_mul_f32 v[28:29], v[28:29], v[184:185]
	v_pk_mul_f32 v[24:25], v[24:25], v[188:189]
	v_pk_mul_f32 v[20:21], v[20:21], v[192:193]
	v_pk_mul_f32 v[30:31], v[30:31], v[186:187]
	v_pk_mul_f32 v[26:27], v[26:27], v[190:191]
	v_pk_mul_f32 v[22:23], v[22:23], v[194:195]
	v_pk_mul_f32 v[18:19], v[18:19], v[218:219]
	v_pk_mul_f32 v[16:17], v[16:17], v[216:217]

.LBB0_1142:
	s_or_b64 exec, exec, s[44:45]
	s_andn2_b64 s[20:21], s[40:41], exec
	s_and_b64 s[40:41], vcc, exec
	s_and_b64 s[44:45], vcc, s[38:39]
	s_or_b64 s[40:41], s[20:21], s[40:41]
	s_and_saveexec_b64 s[20:21], s[44:45]
	s_cbranch_execz .LBB0_1149
	v_max_f32_e32 v0, v80, v81
	v_max3_f32 v0, v0, v82, v83
	v_max3_f32 v0, v0, v84, v85
	v_max3_f32 v0, v0, v86, v87
	v_max3_f32 v0, v0, v88, v89
	v_max3_f32 v0, v0, v90, v91
	v_max3_f32 v0, v0, v92, v93
	v_max3_f32 v0, v0, v94, v95
	v_max3_f32 v0, v0, v96, v97
	v_max3_f32 v0, v0, v98, v99
	v_max3_f32 v0, v0, v100, v101
	v_max3_f32 v0, v0, v102, v103
	v_max3_f32 v0, v0, v104, v105
	v_max3_f32 v0, v0, v106, v107
	v_max3_f32 v0, v0, v108, v109
	v_max3_f32 v0, v0, v110, v111
	v_mov_b32_e32 v2, v0
	s_nop 1
	v_permlane32_swap_b32_e32 v0, v2
	v_max_f32_e32 v0, v0, v2
	v_sub_f32_e32 v2, v0, v173
	v_cmp_ge_f32_e32 vcc, s86, v2
	s_cmp_eq_u64 vcc, exec
	v_max_f32_e32 v2, v173, v0
	s_cselect_b64 vcc, -1, 0
	v_sub_f32_e32 v0, v173, v2
	v_cndmask_b32_e32 v173, v2, v173, vcc
	v_sub_f32_e32 v2, v80, v173
	v_exp_f32_e32 v80, v2
	v_sub_f32_e32 v2, v96, v173
	v_exp_f32_e32 v96, v2
	v_sub_f32_e32 v2, v81, v173
	v_exp_f32_e32 v81, v2
	v_sub_f32_e32 v2, v97, v173
	v_exp_f32_e32 v97, v2
	v_sub_f32_e32 v2, v82, v173
	v_exp_f32_e32 v82, v2
	v_sub_f32_e32 v2, v98, v173
	v_exp_f32_e32 v98, v2
	v_sub_f32_e32 v2, v83, v173
	v_exp_f32_e32 v83, v2
	v_sub_f32_e32 v2, v99, v173
	v_exp_f32_e32 v99, v2
	v_sub_f32_e32 v2, v84, v173
	v_exp_f32_e32 v84, v2
	v_sub_f32_e32 v2, v100, v173
	v_exp_f32_e32 v100, v2
	v_sub_f32_e32 v2, v85, v173
	v_exp_f32_e32 v85, v2
	v_sub_f32_e32 v2, v101, v173
	v_exp_f32_e32 v101, v2
	v_sub_f32_e32 v2, v86, v173
	v_exp_f32_e32 v86, v2
	v_sub_f32_e32 v2, v102, v173
	v_exp_f32_e32 v102, v2
	v_sub_f32_e32 v2, v87, v173
	v_exp_f32_e32 v87, v2
	v_sub_f32_e32 v2, v103, v173
	v_exp_f32_e32 v103, v2
	v_sub_f32_e32 v2, v88, v173
	v_exp_f32_e32 v88, v2
	v_sub_f32_e32 v2, v104, v173
	v_exp_f32_e32 v104, v2
	v_sub_f32_e32 v2, v89, v173
	v_exp_f32_e32 v89, v2
	v_sub_f32_e32 v2, v105, v173
	v_exp_f32_e32 v105, v2
	v_sub_f32_e32 v2, v90, v173
	v_exp_f32_e32 v90, v2
	v_sub_f32_e32 v2, v106, v173
	v_exp_f32_e32 v106, v2
	v_sub_f32_e32 v2, v91, v173
	v_exp_f32_e32 v91, v2
	v_sub_f32_e32 v2, v107, v173
	v_exp_f32_e32 v107, v2
	v_sub_f32_e32 v2, v92, v173
	v_exp_f32_e32 v92, v2
	v_sub_f32_e32 v2, v108, v173
	v_exp_f32_e32 v108, v2
	v_sub_f32_e32 v2, v93, v173
	v_exp_f32_e32 v93, v2
	v_sub_f32_e32 v2, v109, v173
	v_exp_f32_e32 v109, v2
	v_sub_f32_e32 v2, v94, v173
	v_exp_f32_e32 v94, v2
	v_sub_f32_e32 v2, v110, v173
	v_exp_f32_e32 v110, v2
	v_sub_f32_e32 v2, v95, v173
	v_exp_f32_e32 v95, v2
	v_sub_f32_e32 v2, v111, v173
	v_exp_f32_e32 v111, v2
	v_add_f32_e32 v2, v80, v96
	v_add_f32_e32 v2, 0, v2
	v_add_f32_e32 v3, v81, v97
	v_add_f32_e32 v2, v3, v2
	v_add_f32_e32 v3, v82, v98
	v_add_f32_e32 v2, v3, v2
	v_add_f32_e32 v3, v83, v99
	v_add_f32_e32 v2, v3, v2
	v_add_f32_e32 v3, v84, v100
	v_add_f32_e32 v2, v3, v2
	v_add_f32_e32 v3, v85, v101
	v_add_f32_e32 v2, v3, v2
	v_add_f32_e32 v3, v86, v102
	v_add_f32_e32 v2, v3, v2
	v_add_f32_e32 v3, v87, v103
	v_add_f32_e32 v2, v3, v2
	v_add_f32_e32 v3, v88, v104
	v_add_f32_e32 v2, v3, v2
	v_add_f32_e32 v3, v89, v105
	v_add_f32_e32 v2, v3, v2
	v_add_f32_e32 v3, v90, v106
	v_add_f32_e32 v2, v3, v2
	v_add_f32_e32 v3, v91, v107
	v_add_f32_e32 v2, v3, v2
	v_add_f32_e32 v3, v92, v108
	v_add_f32_e32 v2, v3, v2
	v_add_f32_e32 v3, v93, v109
	v_add_f32_e32 v2, v3, v2
	v_add_f32_e32 v3, v94, v110
	v_exp_f32_e32 v0, v0
	v_add_f32_e32 v2, v3, v2
	v_add_f32_e32 v3, v95, v111
	v_add_f32_e32 v14, v3, v2
	v_mov_b32_e32 v15, v14
	v_cvt_pk_bf16_f32 v144, v80, v81
	v_cvt_pk_bf16_f32 v145, v82, v83
	v_cvt_pk_bf16_f32 v146, v84, v85
	v_cvt_pk_bf16_f32 v147, v86, v87
	v_cvt_pk_bf16_f32 v10, v88, v89
	v_cvt_pk_bf16_f32 v11, v90, v91
	v_cvt_pk_bf16_f32 v12, v92, v93
	v_cvt_pk_bf16_f32 v13, v94, v95
	v_cvt_pk_bf16_f32 v6, v96, v97
	v_cvt_pk_bf16_f32 v7, v98, v99
	v_cvt_pk_bf16_f32 v8, v100, v101
	v_cvt_pk_bf16_f32 v9, v102, v103
	v_cvt_pk_bf16_f32 v2, v104, v105
	v_cvt_pk_bf16_f32 v3, v106, v107
	v_cvt_pk_bf16_f32 v4, v108, v109
	v_cvt_pk_bf16_f32 v5, v110, v111
	s_nop 1
	v_permlane32_swap_b32_e32 v14, v15
	v_permlane32_swap_b32_e32 v144, v146
	v_permlane32_swap_b32_e32 v145, v147
	v_permlane32_swap_b32_e32 v10, v12
	v_permlane32_swap_b32_e32 v11, v13
	v_permlane32_swap_b32_e32 v6, v8
	v_permlane32_swap_b32_e32 v7, v9
	v_permlane32_swap_b32_e32 v2, v4
	v_permlane32_swap_b32_e32 v3, v5
	s_cbranch_vccnz .LBB0_1147
	s_and_saveexec_b64 s[44:45], s[16:17]
	ds_write_b32 v168, v0 offset:128
	s_or_b64 exec, exec, s[44:45]
	s_waitcnt lgkmcnt(0)
	v_add_u32_e32 v183, v166, v167
	ds_read_b128 v[184:187], v183 offset:224
	ds_read_b128 v[188:191], v183 offset:192
	ds_read_b128 v[192:195], v183 offset:160
	ds_read_b128 v[216:219], v183 offset:128
	s_waitcnt lgkmcnt(0)
	v_pk_mul_f32 v[76:77], v[76:77], v[184:185]
	v_pk_mul_f32 v[72:73], v[72:73], v[188:189]
	v_pk_mul_f32 v[68:69], v[68:69], v[192:193]
	v_pk_mul_f32 v[78:79], v[78:79], v[186:187]
	v_pk_mul_f32 v[74:75], v[74:75], v[190:191]
	v_pk_mul_f32 v[70:71], v[70:71], v[194:195]
	v_pk_mul_f32 v[66:67], v[66:67], v[218:219]
	v_pk_mul_f32 v[64:65], v[64:65], v[216:217]
	v_pk_mul_f32 v[60:61], v[60:61], v[184:185]
	v_pk_mul_f32 v[56:57], v[56:57], v[188:189]
	v_pk_mul_f32 v[52:53], v[52:53], v[192:193]
	v_pk_mul_f32 v[62:63], v[62:63], v[186:187]
	v_pk_mul_f32 v[58:59], v[58:59], v[190:191]
	v_pk_mul_f32 v[54:55], v[54:55], v[194:195]
	v_pk_mul_f32 v[50:51], v[50:51], v[218:219]
	v_pk_mul_f32 v[48:49], v[48:49], v[216:217]
	v_pk_mul_f32 v[44:45], v[44:45], v[184:185]
	v_pk_mul_f32 v[40:41], v[40:41], v[188:189]
	v_pk_mul_f32 v[36:37], v[36:37], v[192:193]
	v_pk_mul_f32 v[46:47], v[46:47], v[186:187]
	v_pk_mul_f32 v[42:43], v[42:43], v[190:191]
	v_pk_mul_f32 v[38:39], v[38:39], v[194:195]
	v_pk_mul_f32 v[34:35], v[34:35], v[218:219]
	v_pk_mul_f32 v[32:33], v[32:33], v[216:217]
	v_pk_mul_f32 v[28:29], v[28:29], v[184:185]
	v_pk_mul_f32 v[24:25], v[24:25], v[188:189]
	v_pk_mul_f32 v[20:21], v[20:21], v[192:193]
	v_pk_mul_f32 v[30:31], v[30:31], v[186:187]
	v_pk_mul_f32 v[26:27], v[26:27], v[190:191]
	v_pk_mul_f32 v[22:23], v[22:23], v[194:195]
	v_pk_mul_f32 v[18:19], v[18:19], v[218:219]
	v_pk_mul_f32 v[16:17], v[16:17], v[216:217]

.LBB0_1152:
	s_and_b64 s[36:37], s[36:37], s[40:41]
	s_and_saveexec_b64 s[20:21], s[36:37]
	s_cbranch_execz .LBB0_1158
	v_max_f32_e32 v0, v80, v81
	v_max3_f32 v0, v0, v82, v83
	v_max3_f32 v0, v0, v84, v85
	v_max3_f32 v0, v0, v86, v87
	v_max3_f32 v0, v0, v88, v89
	v_max3_f32 v0, v0, v90, v91
	v_max3_f32 v0, v0, v92, v93
	v_max3_f32 v0, v0, v94, v95
	v_max3_f32 v0, v0, v96, v97
	v_max3_f32 v0, v0, v98, v99
	v_max3_f32 v0, v0, v100, v101
	v_max3_f32 v0, v0, v102, v103
	v_max3_f32 v0, v0, v104, v105
	v_max3_f32 v0, v0, v106, v107
	v_max3_f32 v0, v0, v108, v109
	v_max3_f32 v0, v0, v110, v111
	v_mov_b32_e32 v2, v0
	s_nop 1
	v_permlane32_swap_b32_e32 v0, v2
	v_max_f32_e32 v0, v0, v2
	v_sub_f32_e32 v2, v0, v173
	v_cmp_ge_f32_e32 vcc, s86, v2
	s_cmp_eq_u64 vcc, exec
	v_max_f32_e32 v2, v173, v0
	s_cselect_b64 vcc, -1, 0
	v_sub_f32_e32 v0, v173, v2
	v_cndmask_b32_e32 v2, v2, v173, vcc
	v_sub_f32_e32 v10, v99, v2
	v_sub_f32_e32 v11, v100, v2
	v_sub_f32_e32 v12, v101, v2
	v_sub_f32_e32 v13, v102, v2
	v_sub_f32_e32 v14, v103, v2
	v_sub_f32_e32 v4, v96, v2
	v_exp_f32_e32 v96, v10
	v_sub_f32_e32 v10, v84, v2
	v_exp_f32_e32 v84, v11
	v_sub_f32_e32 v11, v85, v2
	v_exp_f32_e32 v85, v12
	v_sub_f32_e32 v12, v86, v2
	v_exp_f32_e32 v86, v13
	v_sub_f32_e32 v13, v87, v2
	v_exp_f32_e32 v87, v14
	v_sub_f32_e32 v14, v88, v2
	v_exp_f32_e32 v88, v14
	v_sub_f32_e32 v14, v104, v2
	v_sub_f32_e32 v6, v97, v2
	v_exp_f32_e32 v97, v14
	v_sub_f32_e32 v14, v89, v2
	v_exp_f32_e32 v89, v14
	v_sub_f32_e32 v14, v105, v2
	v_sub_f32_e32 v8, v98, v2
	v_exp_f32_e32 v98, v14
	v_sub_f32_e32 v14, v90, v2
	v_exp_f32_e32 v90, v14
	v_sub_f32_e32 v14, v106, v2
	v_exp_f32_e32 v99, v14
	v_sub_f32_e32 v14, v91, v2
	v_exp_f32_e32 v91, v14
	v_sub_f32_e32 v14, v107, v2
	v_exp_f32_e32 v100, v14
	v_sub_f32_e32 v14, v92, v2
	v_exp_f32_e32 v92, v14
	v_sub_f32_e32 v14, v108, v2
	v_sub_f32_e32 v3, v80, v2
	v_exp_f32_e32 v101, v14
	v_sub_f32_e32 v14, v93, v2
	v_exp_f32_e32 v3, v3
	v_exp_f32_e32 v4, v4
	v_sub_f32_e32 v5, v81, v2
	v_exp_f32_e32 v93, v14
	v_sub_f32_e32 v14, v109, v2
	v_exp_f32_e32 v5, v5
	v_exp_f32_e32 v6, v6
	v_sub_f32_e32 v7, v82, v2
	v_exp_f32_e32 v102, v14
	v_sub_f32_e32 v14, v94, v2
	v_exp_f32_e32 v7, v7
	v_exp_f32_e32 v8, v8
	v_sub_f32_e32 v9, v83, v2
	v_exp_f32_e32 v94, v14
	v_sub_f32_e32 v14, v110, v2
	v_exp_f32_e32 v9, v9
	v_exp_f32_e32 v103, v14
	v_sub_f32_e32 v14, v95, v2
	v_sub_f32_e32 v2, v111, v2
	v_exp_f32_e32 v10, v10
	v_exp_f32_e32 v104, v2
	v_add_f32_e32 v2, v3, v4
	v_exp_f32_e32 v11, v11
	v_exp_f32_e32 v95, v14
	v_add_f32_e32 v2, 0, v2
	v_add_f32_e32 v14, v5, v6
	v_exp_f32_e32 v12, v12
	v_add_f32_e32 v2, v14, v2
	v_add_f32_e32 v14, v7, v8
	v_exp_f32_e32 v13, v13
	v_add_f32_e32 v2, v14, v2
	v_add_f32_e32 v14, v9, v96
	v_add_f32_e32 v2, v14, v2
	v_add_f32_e32 v14, v10, v84
	v_add_f32_e32 v2, v14, v2
	v_add_f32_e32 v14, v11, v85
	v_add_f32_e32 v2, v14, v2
	v_add_f32_e32 v14, v12, v86
	v_add_f32_e32 v2, v14, v2
	v_add_f32_e32 v14, v13, v87
	v_add_f32_e32 v2, v14, v2
	v_add_f32_e32 v14, v88, v97
	v_add_f32_e32 v2, v14, v2
	v_add_f32_e32 v14, v89, v98
	v_add_f32_e32 v2, v14, v2
	v_add_f32_e32 v14, v90, v99
	v_add_f32_e32 v2, v14, v2
	v_add_f32_e32 v14, v91, v100
	v_add_f32_e32 v2, v14, v2
	v_add_f32_e32 v14, v92, v101
	v_add_f32_e32 v2, v14, v2
	v_add_f32_e32 v14, v93, v102
	v_add_f32_e32 v2, v14, v2
	v_add_f32_e32 v14, v94, v103
	v_exp_f32_e32 v0, v0
	v_add_f32_e32 v2, v14, v2
	v_add_f32_e32 v14, v95, v104
	v_add_f32_e32 v14, v14, v2
	v_mov_b32_e32 v15, v14
	v_cvt_pk_bf16_f32 v80, v3, v5
	v_cvt_pk_bf16_f32 v81, v7, v9
	v_cvt_pk_bf16_f32 v82, v10, v11
	v_cvt_pk_bf16_f32 v83, v12, v13
	v_cvt_pk_bf16_f32 v10, v88, v89
	v_cvt_pk_bf16_f32 v11, v90, v91
	v_cvt_pk_bf16_f32 v12, v92, v93
	v_cvt_pk_bf16_f32 v13, v94, v95
	v_cvt_pk_bf16_f32 v6, v4, v6
	v_cvt_pk_bf16_f32 v7, v8, v96
	v_cvt_pk_bf16_f32 v8, v84, v85
	v_cvt_pk_bf16_f32 v9, v86, v87
	v_cvt_pk_bf16_f32 v2, v97, v98
	v_cvt_pk_bf16_f32 v3, v99, v100
	v_cvt_pk_bf16_f32 v4, v101, v102
	v_cvt_pk_bf16_f32 v5, v103, v104
	s_nop 1
	v_permlane32_swap_b32_e32 v14, v15
	v_permlane32_swap_b32_e32 v80, v82
	v_permlane32_swap_b32_e32 v81, v83
	v_permlane32_swap_b32_e32 v10, v12
	v_permlane32_swap_b32_e32 v11, v13
	v_permlane32_swap_b32_e32 v6, v8
	v_permlane32_swap_b32_e32 v7, v9
	v_permlane32_swap_b32_e32 v2, v4
	v_permlane32_swap_b32_e32 v3, v5
	s_cbranch_vccnz .LBB0_1157
	s_and_saveexec_b64 s[36:37], s[16:17]
	ds_write_b32 v168, v0 offset:128
	s_or_b64 exec, exec, s[36:37]
	s_waitcnt lgkmcnt(0)
	v_add_u32_e32 v96, v166, v167
	ds_read_b128 v[84:87], v96 offset:224
	ds_read_b128 v[88:91], v96 offset:192
	ds_read_b128 v[92:95], v96 offset:160
	ds_read_b128 v[96:99], v96 offset:128
	s_waitcnt lgkmcnt(3)
	v_pk_mul_f32 v[76:77], v[76:77], v[84:85]
	s_waitcnt lgkmcnt(2)
	v_pk_mul_f32 v[72:73], v[72:73], v[88:89]
	s_waitcnt lgkmcnt(1)
	v_pk_mul_f32 v[68:69], v[68:69], v[92:93]
	v_pk_mul_f32 v[78:79], v[78:79], v[86:87]
	v_pk_mul_f32 v[74:75], v[74:75], v[90:91]
	v_pk_mul_f32 v[70:71], v[70:71], v[94:95]
	s_waitcnt lgkmcnt(0)
	v_pk_mul_f32 v[66:67], v[66:67], v[98:99]
	v_pk_mul_f32 v[64:65], v[64:65], v[96:97]
	v_pk_mul_f32 v[60:61], v[60:61], v[84:85]
	v_pk_mul_f32 v[56:57], v[56:57], v[88:89]
	v_pk_mul_f32 v[52:53], v[52:53], v[92:93]
	v_pk_mul_f32 v[62:63], v[62:63], v[86:87]
	v_pk_mul_f32 v[58:59], v[58:59], v[90:91]
	v_pk_mul_f32 v[54:55], v[54:55], v[94:95]
	v_pk_mul_f32 v[50:51], v[50:51], v[98:99]
	v_pk_mul_f32 v[48:49], v[48:49], v[96:97]
	v_pk_mul_f32 v[44:45], v[44:45], v[84:85]
	v_pk_mul_f32 v[40:41], v[40:41], v[88:89]
	v_pk_mul_f32 v[36:37], v[36:37], v[92:93]
	v_pk_mul_f32 v[46:47], v[46:47], v[86:87]
	v_pk_mul_f32 v[42:43], v[42:43], v[90:91]
	v_pk_mul_f32 v[38:39], v[38:39], v[94:95]
	v_pk_mul_f32 v[34:35], v[34:35], v[98:99]
	v_pk_mul_f32 v[32:33], v[32:33], v[96:97]
	v_pk_mul_f32 v[28:29], v[28:29], v[84:85]
	v_pk_mul_f32 v[24:25], v[24:25], v[88:89]
	v_pk_mul_f32 v[20:21], v[20:21], v[92:93]
	v_pk_mul_f32 v[30:31], v[30:31], v[86:87]
	v_pk_mul_f32 v[26:27], v[26:27], v[90:91]
	v_pk_mul_f32 v[22:23], v[22:23], v[94:95]
	v_pk_mul_f32 v[18:19], v[18:19], v[98:99]
	v_pk_mul_f32 v[16:17], v[16:17], v[96:97]

.LBB0_1166:
	s_and_b64 s[14:15], s[8:9], s[14:15]
	s_andn2_b64 vcc, exec, s[14:15]
	s_cbranch_vccnz .LBB0_1172
	v_max_f32_e32 v0, v96, v97
	v_max3_f32 v0, v0, v98, v99
	v_max3_f32 v0, v0, v100, v101
	v_max3_f32 v0, v0, v102, v103
	v_max3_f32 v0, v0, v104, v105
	v_max3_f32 v0, v0, v106, v107
	v_max3_f32 v0, v0, v108, v109
	v_max3_f32 v0, v0, v110, v111
	v_max3_f32 v0, v0, v80, v81
	v_max3_f32 v0, v0, v82, v83
	v_max3_f32 v0, v0, v84, v85
	v_max3_f32 v0, v0, v86, v87
	v_max3_f32 v0, v0, v88, v89
	v_max3_f32 v0, v0, v90, v91
	v_max3_f32 v0, v0, v92, v93
	v_max3_f32 v0, v0, v94, v95
	v_mov_b32_e32 v2, v0
	s_nop 1
	v_permlane32_swap_b32_e32 v0, v2
	v_max_f32_e32 v0, v0, v2
	v_sub_f32_e32 v2, v0, v158
	v_cmp_ge_f32_e32 vcc, s86, v2
	s_cmp_eq_u64 vcc, exec
	v_max_f32_e32 v2, v158, v0
	s_cselect_b64 vcc, -1, 0
	v_sub_f32_e32 v0, v158, v2
	v_cndmask_b32_e32 v158, v2, v158, vcc
	v_sub_f32_e32 v14, v87, v158
	v_exp_f32_e32 v87, v14
	v_sub_f32_e32 v14, v104, v158
	v_sub_f32_e32 v2, v96, v158
	v_exp_f32_e32 v96, v14
	v_sub_f32_e32 v14, v88, v158
	v_exp_f32_e32 v88, v14
	v_sub_f32_e32 v14, v105, v158
	v_sub_f32_e32 v4, v97, v158
	v_exp_f32_e32 v97, v14
	v_sub_f32_e32 v14, v89, v158
	v_exp_f32_e32 v89, v14
	v_sub_f32_e32 v14, v106, v158
	v_sub_f32_e32 v6, v98, v158
	v_exp_f32_e32 v98, v14
	v_sub_f32_e32 v14, v90, v158
	v_exp_f32_e32 v90, v14
	v_sub_f32_e32 v14, v107, v158
	v_sub_f32_e32 v8, v99, v158
	v_exp_f32_e32 v99, v14
	v_sub_f32_e32 v14, v91, v158
	v_exp_f32_e32 v91, v14
	v_sub_f32_e32 v14, v108, v158
	v_sub_f32_e32 v10, v100, v158
	v_exp_f32_e32 v100, v14
	v_sub_f32_e32 v14, v92, v158
	v_sub_f32_e32 v11, v84, v158
	v_exp_f32_e32 v92, v14
	v_sub_f32_e32 v14, v109, v158
	v_sub_f32_e32 v3, v80, v158
	v_exp_f32_e32 v84, v11
	v_sub_f32_e32 v11, v101, v158
	v_exp_f32_e32 v101, v14
	v_sub_f32_e32 v14, v93, v158
	v_exp_f32_e32 v2, v2
	v_exp_f32_e32 v3, v3
	v_sub_f32_e32 v5, v81, v158
	v_sub_f32_e32 v12, v85, v158
	v_exp_f32_e32 v93, v14
	v_sub_f32_e32 v14, v110, v158
	v_exp_f32_e32 v4, v4
	v_exp_f32_e32 v5, v5
	v_sub_f32_e32 v7, v82, v158
	v_exp_f32_e32 v85, v12
	v_sub_f32_e32 v12, v102, v158
	v_exp_f32_e32 v102, v14
	v_sub_f32_e32 v14, v94, v158
	v_exp_f32_e32 v6, v6
	v_exp_f32_e32 v7, v7
	v_sub_f32_e32 v9, v83, v158
	v_sub_f32_e32 v13, v86, v158
	v_exp_f32_e32 v94, v14
	v_sub_f32_e32 v14, v111, v158
	v_exp_f32_e32 v8, v8
	v_exp_f32_e32 v9, v9
	v_exp_f32_e32 v86, v13
	v_sub_f32_e32 v13, v103, v158
	v_exp_f32_e32 v103, v14
	v_sub_f32_e32 v14, v95, v158
	v_exp_f32_e32 v10, v10
	v_exp_f32_e32 v95, v14
	v_add_f32_e32 v14, v2, v3
	v_exp_f32_e32 v11, v11
	v_add_f32_e32 v14, 0, v14
	v_add_f32_e32 v15, v4, v5
	v_exp_f32_e32 v12, v12
	v_add_f32_e32 v14, v15, v14
	v_add_f32_e32 v15, v6, v7
	v_exp_f32_e32 v13, v13
	v_add_f32_e32 v14, v15, v14
	v_add_f32_e32 v15, v8, v9
	v_add_f32_e32 v14, v15, v14
	v_add_f32_e32 v15, v10, v84
	v_add_f32_e32 v14, v15, v14
	v_add_f32_e32 v15, v11, v85
	v_add_f32_e32 v14, v15, v14
	v_add_f32_e32 v15, v12, v86
	v_add_f32_e32 v14, v15, v14
	v_add_f32_e32 v15, v13, v87
	v_add_f32_e32 v14, v15, v14
	v_add_f32_e32 v15, v96, v88
	v_add_f32_e32 v14, v15, v14
	v_add_f32_e32 v15, v97, v89
	v_add_f32_e32 v14, v15, v14
	v_add_f32_e32 v15, v98, v90
	v_add_f32_e32 v14, v15, v14
	v_add_f32_e32 v15, v99, v91
	v_add_f32_e32 v14, v15, v14
	v_add_f32_e32 v15, v100, v92
	v_add_f32_e32 v14, v15, v14
	v_add_f32_e32 v15, v101, v93
	v_add_f32_e32 v14, v15, v14
	v_add_f32_e32 v15, v102, v94
	v_exp_f32_e32 v0, v0
	v_add_f32_e32 v14, v15, v14
	v_add_f32_e32 v15, v103, v95
	v_add_f32_e32 v14, v15, v14
	v_mov_b32_e32 v15, v14
	v_cvt_pk_bf16_f32 v80, v2, v4
	v_cvt_pk_bf16_f32 v81, v6, v8
	v_cvt_pk_bf16_f32 v82, v10, v11
	v_cvt_pk_bf16_f32 v83, v12, v13
	v_cvt_pk_bf16_f32 v10, v96, v97
	v_cvt_pk_bf16_f32 v11, v98, v99
	v_cvt_pk_bf16_f32 v12, v100, v101
	v_cvt_pk_bf16_f32 v13, v102, v103
	v_cvt_pk_bf16_f32 v6, v3, v5
	v_cvt_pk_bf16_f32 v7, v7, v9
	v_cvt_pk_bf16_f32 v8, v84, v85
	v_cvt_pk_bf16_f32 v9, v86, v87
	v_cvt_pk_bf16_f32 v2, v88, v89
	v_cvt_pk_bf16_f32 v3, v90, v91
	v_cvt_pk_bf16_f32 v4, v92, v93
	v_cvt_pk_bf16_f32 v5, v94, v95
	s_nop 1
	v_permlane32_swap_b32_e32 v14, v15
	v_permlane32_swap_b32_e32 v80, v82
	v_permlane32_swap_b32_e32 v81, v83
	v_permlane32_swap_b32_e32 v10, v12
	v_permlane32_swap_b32_e32 v11, v13
	v_permlane32_swap_b32_e32 v6, v8
	v_permlane32_swap_b32_e32 v7, v9
	v_permlane32_swap_b32_e32 v2, v4
	v_permlane32_swap_b32_e32 v3, v5
	s_cbranch_vccnz .LBB0_1171
	s_and_saveexec_b64 s[14:15], s[0:1]
	ds_write_b32 v154, v0 offset:128
	s_or_b64 exec, exec, s[14:15]
	s_waitcnt lgkmcnt(0)
	v_add_u32_e32 v96, v151, v153
	ds_read_b128 v[84:87], v96 offset:224
	ds_read_b128 v[88:91], v96 offset:192
	ds_read_b128 v[92:95], v96 offset:160
	ds_read_b128 v[96:99], v96 offset:128
	s_waitcnt lgkmcnt(0)
	v_pk_mul_f32 v[76:77], v[76:77], v[84:85]
	v_pk_mul_f32 v[72:73], v[72:73], v[88:89]
	v_pk_mul_f32 v[68:69], v[68:69], v[92:93]
	v_pk_mul_f32 v[78:79], v[78:79], v[86:87]
	v_pk_mul_f32 v[74:75], v[74:75], v[90:91]
	v_pk_mul_f32 v[70:71], v[70:71], v[94:95]
	v_pk_mul_f32 v[66:67], v[66:67], v[98:99]
	v_pk_mul_f32 v[64:65], v[64:65], v[96:97]
	v_pk_mul_f32 v[60:61], v[60:61], v[84:85]
	v_pk_mul_f32 v[56:57], v[56:57], v[88:89]
	v_pk_mul_f32 v[52:53], v[52:53], v[92:93]
	v_pk_mul_f32 v[62:63], v[62:63], v[86:87]
	v_pk_mul_f32 v[58:59], v[58:59], v[90:91]
	v_pk_mul_f32 v[54:55], v[54:55], v[94:95]
	v_pk_mul_f32 v[50:51], v[50:51], v[98:99]
	v_pk_mul_f32 v[48:49], v[48:49], v[96:97]
	v_pk_mul_f32 v[44:45], v[44:45], v[84:85]
	v_pk_mul_f32 v[40:41], v[40:41], v[88:89]
	v_pk_mul_f32 v[36:37], v[36:37], v[92:93]
	v_pk_mul_f32 v[46:47], v[46:47], v[86:87]
	v_pk_mul_f32 v[42:43], v[42:43], v[90:91]
	v_pk_mul_f32 v[38:39], v[38:39], v[94:95]
	v_pk_mul_f32 v[34:35], v[34:35], v[98:99]
	v_pk_mul_f32 v[32:33], v[32:33], v[96:97]
	v_pk_mul_f32 v[28:29], v[28:29], v[84:85]
	v_pk_mul_f32 v[24:25], v[24:25], v[88:89]
	v_pk_mul_f32 v[20:21], v[20:21], v[92:93]
	v_pk_mul_f32 v[30:31], v[30:31], v[86:87]
	v_pk_mul_f32 v[26:27], v[26:27], v[90:91]
	v_pk_mul_f32 v[22:23], v[22:23], v[94:95]
	v_pk_mul_f32 v[18:19], v[18:19], v[98:99]
	v_pk_mul_f32 v[16:17], v[16:17], v[96:97]

.LBB0_1172:
	s_lshl_b32 s14, s34, 14
	s_add_i32 s14, s14, 0
	s_add_i32 s14, s14, 0x10000
	v_add3_u32 v0, s14, v157, v156
	v_add3_u32 v6, s14, v159, v156
	v_add3_u32 v7, s14, v160, v156
	v_add3_u32 v8, s14, v161, v156
	ds_read_b128 v[216:219], v0
	ds_read_b128 v[220:223], v0 offset:8192
	ds_read_b128 v[224:227], v6
	ds_read_b128 v[228:231], v6 offset:8192
	ds_read_b128 v[232:235], v7
	ds_read_b128 v[236:239], v7 offset:8192
	ds_read_b128 v[240:243], v8
	ds_read_b128 v[244:247], v8 offset:8192
	s_waitcnt lgkmcnt(6)
	v_mfma_f32_32x32x16_bf16 v[96:111], v[216:219], v[112:115], 0
	v_mfma_f32_32x32x16_bf16 v[80:95], v[220:223], v[112:115], 0
	ds_read_b128 v[216:219], v0 offset:128
	ds_read_b128 v[220:223], v0 offset:8320
	s_waitcnt lgkmcnt(6)
	v_mfma_f32_32x32x16_bf16 v[96:111], v[224:227], v[116:119], v[96:111]
	v_mfma_f32_32x32x16_bf16 v[80:95], v[228:231], v[116:119], v[80:95]
	ds_read_b128 v[224:227], v6 offset:128
	ds_read_b128 v[228:231], v6 offset:8320
	s_waitcnt lgkmcnt(6)
	v_mfma_f32_32x32x16_bf16 v[96:111], v[232:235], v[120:123], v[96:111]
	v_mfma_f32_32x32x16_bf16 v[80:95], v[236:239], v[120:123], v[80:95]
	ds_read_b128 v[232:235], v7 offset:128
	ds_read_b128 v[236:239], v7 offset:8320
	s_waitcnt lgkmcnt(6)
	v_mfma_f32_32x32x16_bf16 v[96:111], v[240:243], v[124:127], v[96:111]
	v_mfma_f32_32x32x16_bf16 v[80:95], v[244:247], v[124:127], v[80:95]
	ds_read_b128 v[240:243], v8 offset:128
	ds_read_b128 v[244:247], v8 offset:8320
	s_andn2_b64 vcc, exec, s[10:11]
	s_waitcnt lgkmcnt(6)
	v_mfma_f32_32x32x16_bf16 v[96:111], v[216:219], v[128:131], v[96:111]
	v_mfma_f32_32x32x16_bf16 v[80:95], v[220:223], v[128:131], v[80:95]
	s_waitcnt lgkmcnt(4)
	v_mfma_f32_32x32x16_bf16 v[96:111], v[224:227], v[132:135], v[96:111]
	v_mfma_f32_32x32x16_bf16 v[80:95], v[228:231], v[132:135], v[80:95]
	s_waitcnt lgkmcnt(2)
	v_mfma_f32_32x32x16_bf16 v[96:111], v[232:235], v[136:139], v[96:111]
	v_mfma_f32_32x32x16_bf16 v[80:95], v[236:239], v[136:139], v[80:95]
	s_waitcnt lgkmcnt(0)
	v_mfma_f32_32x32x16_bf16 v[96:111], v[240:243], v[140:143], v[96:111]
	v_mfma_f32_32x32x16_bf16 v[80:95], v[244:247], v[140:143], v[80:95]
	s_nop 1
	s_cbranch_vccnz .LBB0_1182
	s_nop 7
	v_max_f32_e32 v0, v96, v97
	v_max3_f32 v0, v0, v98, v99
	v_max3_f32 v0, v0, v100, v101
	v_max3_f32 v0, v0, v102, v103
	v_max3_f32 v0, v0, v104, v105
	v_max3_f32 v0, v0, v106, v107
	v_max3_f32 v0, v0, v108, v109
	v_max3_f32 v0, v0, v110, v111
	v_max3_f32 v0, v0, v80, v81
	v_max3_f32 v0, v0, v82, v83
	v_max3_f32 v0, v0, v84, v85
	v_max3_f32 v0, v0, v86, v87
	v_max3_f32 v0, v0, v88, v89
	v_max3_f32 v0, v0, v90, v91
	v_max3_f32 v0, v0, v92, v93
	v_max3_f32 v0, v0, v94, v95
	v_mov_b32_e32 v2, v0
	s_nop 1
	v_permlane32_swap_b32_e32 v0, v2
	v_max_f32_e32 v0, v0, v2
	v_sub_f32_e32 v2, v0, v158
	v_cmp_ge_f32_e32 vcc, s86, v2
	s_cmp_eq_u64 vcc, exec
	v_max_f32_e32 v2, v158, v0
	s_cselect_b64 vcc, -1, 0
	v_sub_f32_e32 v0, v158, v2
	v_cndmask_b32_e32 v158, v2, v158, vcc
	v_sub_f32_e32 v2, v96, v158
	v_exp_f32_e32 v96, v2
	v_sub_f32_e32 v2, v80, v158
	v_exp_f32_e32 v80, v2
	v_sub_f32_e32 v2, v97, v158
	v_exp_f32_e32 v97, v2
	v_sub_f32_e32 v2, v81, v158
	v_exp_f32_e32 v81, v2
	v_sub_f32_e32 v2, v98, v158
	v_exp_f32_e32 v98, v2
	v_sub_f32_e32 v2, v82, v158
	v_exp_f32_e32 v82, v2
	v_sub_f32_e32 v2, v99, v158
	v_exp_f32_e32 v99, v2
	v_sub_f32_e32 v2, v83, v158
	v_exp_f32_e32 v83, v2
	v_sub_f32_e32 v2, v100, v158
	v_exp_f32_e32 v100, v2
	v_sub_f32_e32 v2, v84, v158
	v_exp_f32_e32 v84, v2
	v_sub_f32_e32 v2, v101, v158
	v_exp_f32_e32 v101, v2
	v_sub_f32_e32 v2, v85, v158
	v_exp_f32_e32 v85, v2
	v_sub_f32_e32 v2, v102, v158
	v_exp_f32_e32 v102, v2
	v_sub_f32_e32 v2, v86, v158
	v_exp_f32_e32 v86, v2
	v_sub_f32_e32 v2, v103, v158
	v_exp_f32_e32 v103, v2
	v_sub_f32_e32 v2, v87, v158
	v_exp_f32_e32 v87, v2
	v_sub_f32_e32 v2, v104, v158
	v_exp_f32_e32 v104, v2
	v_sub_f32_e32 v2, v88, v158
	v_exp_f32_e32 v88, v2
	v_sub_f32_e32 v2, v105, v158
	v_exp_f32_e32 v105, v2
	v_sub_f32_e32 v2, v89, v158
	v_exp_f32_e32 v89, v2
	v_sub_f32_e32 v2, v106, v158
	v_exp_f32_e32 v106, v2
	v_sub_f32_e32 v2, v90, v158
	v_exp_f32_e32 v90, v2
	v_sub_f32_e32 v2, v107, v158
	v_exp_f32_e32 v107, v2
	v_sub_f32_e32 v2, v91, v158
	v_exp_f32_e32 v91, v2
	v_sub_f32_e32 v2, v108, v158
	v_exp_f32_e32 v108, v2
	v_sub_f32_e32 v2, v92, v158
	v_exp_f32_e32 v92, v2
	v_sub_f32_e32 v2, v109, v158
	v_exp_f32_e32 v109, v2
	v_sub_f32_e32 v2, v93, v158
	v_exp_f32_e32 v93, v2
	v_sub_f32_e32 v2, v110, v158
	v_exp_f32_e32 v110, v2
	v_sub_f32_e32 v2, v94, v158
	v_exp_f32_e32 v94, v2
	v_sub_f32_e32 v2, v111, v158
	v_exp_f32_e32 v111, v2
	v_sub_f32_e32 v2, v95, v158
	v_exp_f32_e32 v95, v2
	v_add_f32_e32 v2, v96, v80
	v_add_f32_e32 v2, 0, v2
	v_add_f32_e32 v3, v97, v81
	v_add_f32_e32 v2, v3, v2
	v_add_f32_e32 v3, v98, v82
	v_add_f32_e32 v2, v3, v2
	v_add_f32_e32 v3, v99, v83
	v_add_f32_e32 v2, v3, v2
	v_add_f32_e32 v3, v100, v84
	v_add_f32_e32 v2, v3, v2
	v_add_f32_e32 v3, v101, v85
	v_add_f32_e32 v2, v3, v2
	v_add_f32_e32 v3, v102, v86
	v_add_f32_e32 v2, v3, v2
	v_add_f32_e32 v3, v103, v87
	v_add_f32_e32 v2, v3, v2
	v_add_f32_e32 v3, v104, v88
	v_add_f32_e32 v2, v3, v2
	v_add_f32_e32 v3, v105, v89
	v_add_f32_e32 v2, v3, v2
	v_add_f32_e32 v3, v106, v90
	v_add_f32_e32 v2, v3, v2
	v_add_f32_e32 v3, v107, v91
	v_add_f32_e32 v2, v3, v2
	v_add_f32_e32 v3, v108, v92
	v_add_f32_e32 v2, v3, v2
	v_add_f32_e32 v3, v109, v93
	v_add_f32_e32 v2, v3, v2
	v_add_f32_e32 v3, v110, v94
	v_exp_f32_e32 v0, v0
	v_add_f32_e32 v2, v3, v2
	v_add_f32_e32 v3, v111, v95
	v_add_f32_e32 v14, v3, v2
	v_mov_b32_e32 v15, v14
	v_cvt_pk_bf16_f32 v144, v96, v97
	v_cvt_pk_bf16_f32 v145, v98, v99
	v_cvt_pk_bf16_f32 v146, v100, v101
	v_cvt_pk_bf16_f32 v147, v102, v103
	v_cvt_pk_bf16_f32 v10, v104, v105
	v_cvt_pk_bf16_f32 v11, v106, v107
	v_cvt_pk_bf16_f32 v12, v108, v109
	v_cvt_pk_bf16_f32 v13, v110, v111
	v_cvt_pk_bf16_f32 v6, v80, v81
	v_cvt_pk_bf16_f32 v7, v82, v83
	v_cvt_pk_bf16_f32 v8, v84, v85
	v_cvt_pk_bf16_f32 v9, v86, v87
	v_cvt_pk_bf16_f32 v2, v88, v89
	v_cvt_pk_bf16_f32 v3, v90, v91
	v_cvt_pk_bf16_f32 v4, v92, v93
	v_cvt_pk_bf16_f32 v5, v94, v95
	s_nop 1
	v_permlane32_swap_b32_e32 v14, v15
	v_permlane32_swap_b32_e32 v144, v146
	v_permlane32_swap_b32_e32 v145, v147
	v_permlane32_swap_b32_e32 v10, v12
	v_permlane32_swap_b32_e32 v11, v13
	v_permlane32_swap_b32_e32 v6, v8
	v_permlane32_swap_b32_e32 v7, v9
	v_permlane32_swap_b32_e32 v2, v4
	v_permlane32_swap_b32_e32 v3, v5
	s_cbranch_vccnz .LBB0_1177
	s_and_saveexec_b64 s[14:15], s[0:1]
	ds_write_b32 v154, v0 offset:128
	s_or_b64 exec, exec, s[14:15]
	s_waitcnt lgkmcnt(0)
	v_add_u32_e32 v165, v151, v153
	ds_read_b128 v[166:169], v165 offset:224
	ds_read_b128 v[170:173], v165 offset:192
	ds_read_b128 v[174:177], v165 offset:160
	ds_read_b128 v[180:183], v165 offset:128
	s_waitcnt lgkmcnt(0)
	v_pk_mul_f32 v[76:77], v[76:77], v[166:167]
	v_pk_mul_f32 v[72:73], v[72:73], v[170:171]
	v_pk_mul_f32 v[68:69], v[68:69], v[174:175]
	v_pk_mul_f32 v[78:79], v[78:79], v[168:169]
	v_pk_mul_f32 v[74:75], v[74:75], v[172:173]
	v_pk_mul_f32 v[70:71], v[70:71], v[176:177]
	v_pk_mul_f32 v[66:67], v[66:67], v[182:183]
	v_pk_mul_f32 v[64:65], v[64:65], v[180:181]
	v_pk_mul_f32 v[60:61], v[60:61], v[166:167]
	v_pk_mul_f32 v[56:57], v[56:57], v[170:171]
	v_pk_mul_f32 v[52:53], v[52:53], v[174:175]
	v_pk_mul_f32 v[62:63], v[62:63], v[168:169]
	v_pk_mul_f32 v[58:59], v[58:59], v[172:173]
	v_pk_mul_f32 v[54:55], v[54:55], v[176:177]
	v_pk_mul_f32 v[50:51], v[50:51], v[182:183]
	v_pk_mul_f32 v[48:49], v[48:49], v[180:181]
	v_pk_mul_f32 v[44:45], v[44:45], v[166:167]
	v_pk_mul_f32 v[40:41], v[40:41], v[170:171]
	v_pk_mul_f32 v[36:37], v[36:37], v[174:175]
	v_pk_mul_f32 v[46:47], v[46:47], v[168:169]
	v_pk_mul_f32 v[42:43], v[42:43], v[172:173]
	v_pk_mul_f32 v[38:39], v[38:39], v[176:177]
	v_pk_mul_f32 v[34:35], v[34:35], v[182:183]
	v_pk_mul_f32 v[32:33], v[32:33], v[180:181]
	v_pk_mul_f32 v[28:29], v[28:29], v[166:167]
	v_pk_mul_f32 v[24:25], v[24:25], v[170:171]
	v_pk_mul_f32 v[20:21], v[20:21], v[174:175]
	v_pk_mul_f32 v[30:31], v[30:31], v[168:169]
	v_pk_mul_f32 v[26:27], v[26:27], v[172:173]
	v_pk_mul_f32 v[22:23], v[22:23], v[176:177]
	v_pk_mul_f32 v[18:19], v[18:19], v[182:183]
	v_pk_mul_f32 v[16:17], v[16:17], v[180:181]

.LBB0_1184:
	s_andn2_b64 vcc, exec, s[8:9]
	s_cbranch_vccnz .LBB0_1190
	v_max_f32_e32 v0, v96, v97
	v_max3_f32 v0, v0, v98, v99
	v_max3_f32 v0, v0, v100, v101
	v_max3_f32 v0, v0, v102, v103
	v_max3_f32 v0, v0, v104, v105
	v_max3_f32 v0, v0, v106, v107
	v_max3_f32 v0, v0, v108, v109
	v_max3_f32 v0, v0, v110, v111
	v_max3_f32 v0, v0, v80, v81
	v_max3_f32 v0, v0, v82, v83
	v_max3_f32 v0, v0, v84, v85
	v_max3_f32 v0, v0, v86, v87
	v_max3_f32 v0, v0, v88, v89
	v_max3_f32 v0, v0, v90, v91
	v_max3_f32 v0, v0, v92, v93
	v_max3_f32 v0, v0, v94, v95
	v_mov_b32_e32 v2, v0
	s_nop 1
	v_permlane32_swap_b32_e32 v0, v2
	v_max_f32_e32 v0, v0, v2
	v_sub_f32_e32 v2, v0, v158
	v_cmp_ge_f32_e32 vcc, s86, v2
	s_cmp_eq_u64 vcc, exec
	v_max_f32_e32 v2, v158, v0
	s_cselect_b64 vcc, -1, 0
	v_sub_f32_e32 v0, v158, v2
	v_cndmask_b32_e32 v2, v2, v158, vcc
	v_sub_f32_e32 v14, v87, v2
	v_exp_f32_e32 v87, v14
	v_sub_f32_e32 v14, v104, v2
	v_sub_f32_e32 v5, v97, v2
	v_exp_f32_e32 v97, v14
	v_sub_f32_e32 v14, v88, v2
	v_exp_f32_e32 v88, v14
	v_sub_f32_e32 v14, v105, v2
	v_sub_f32_e32 v7, v98, v2
	v_exp_f32_e32 v98, v14
	v_sub_f32_e32 v14, v89, v2
	v_exp_f32_e32 v89, v14
	v_sub_f32_e32 v14, v106, v2
	v_sub_f32_e32 v9, v99, v2
	v_exp_f32_e32 v99, v14
	v_sub_f32_e32 v14, v90, v2
	v_sub_f32_e32 v10, v83, v2
	v_exp_f32_e32 v90, v14
	v_sub_f32_e32 v14, v107, v2
	v_sub_f32_e32 v3, v96, v2
	v_exp_f32_e32 v96, v10
	v_sub_f32_e32 v10, v100, v2
	v_exp_f32_e32 v100, v14
	v_sub_f32_e32 v14, v91, v2
	v_sub_f32_e32 v11, v84, v2
	v_exp_f32_e32 v91, v14
	v_sub_f32_e32 v14, v108, v2
	v_exp_f32_e32 v84, v11
	v_sub_f32_e32 v11, v101, v2
	v_exp_f32_e32 v101, v14
	v_sub_f32_e32 v14, v92, v2
	v_sub_f32_e32 v4, v80, v2
	v_sub_f32_e32 v12, v85, v2
	v_exp_f32_e32 v92, v14
	v_sub_f32_e32 v14, v109, v2
	v_exp_f32_e32 v3, v3
	v_exp_f32_e32 v4, v4
	v_sub_f32_e32 v6, v81, v2
	v_exp_f32_e32 v85, v12
	v_sub_f32_e32 v12, v102, v2
	v_exp_f32_e32 v102, v14
	v_sub_f32_e32 v14, v93, v2
	v_exp_f32_e32 v5, v5
	v_exp_f32_e32 v6, v6
	v_sub_f32_e32 v8, v82, v2
	v_sub_f32_e32 v13, v86, v2
	v_exp_f32_e32 v93, v14
	v_sub_f32_e32 v14, v110, v2
	v_exp_f32_e32 v7, v7
	v_exp_f32_e32 v8, v8
	v_exp_f32_e32 v86, v13
	v_sub_f32_e32 v13, v103, v2
	v_exp_f32_e32 v103, v14
	v_sub_f32_e32 v14, v94, v2
	v_exp_f32_e32 v9, v9
	v_exp_f32_e32 v94, v14
	v_sub_f32_e32 v14, v111, v2
	v_sub_f32_e32 v2, v95, v2
	v_exp_f32_e32 v10, v10
	v_exp_f32_e32 v95, v2
	v_add_f32_e32 v2, v3, v4
	v_exp_f32_e32 v11, v11
	v_exp_f32_e32 v104, v14
	v_add_f32_e32 v2, 0, v2
	v_add_f32_e32 v14, v5, v6
	v_exp_f32_e32 v12, v12
	v_add_f32_e32 v2, v14, v2
	v_add_f32_e32 v14, v7, v8
	v_exp_f32_e32 v13, v13
	v_add_f32_e32 v2, v14, v2
	v_add_f32_e32 v14, v9, v96
	v_add_f32_e32 v2, v14, v2
	v_add_f32_e32 v14, v10, v84
	v_add_f32_e32 v2, v14, v2
	v_add_f32_e32 v14, v11, v85
	v_add_f32_e32 v2, v14, v2
	v_add_f32_e32 v14, v12, v86
	v_add_f32_e32 v2, v14, v2
	v_add_f32_e32 v14, v13, v87
	v_add_f32_e32 v2, v14, v2
	v_add_f32_e32 v14, v97, v88
	v_add_f32_e32 v2, v14, v2
	v_add_f32_e32 v14, v98, v89
	v_add_f32_e32 v2, v14, v2
	v_add_f32_e32 v14, v99, v90
	v_add_f32_e32 v2, v14, v2
	v_add_f32_e32 v14, v100, v91
	v_add_f32_e32 v2, v14, v2
	v_add_f32_e32 v14, v101, v92
	v_add_f32_e32 v2, v14, v2
	v_add_f32_e32 v14, v102, v93
	v_add_f32_e32 v2, v14, v2
	v_add_f32_e32 v14, v103, v94
	v_exp_f32_e32 v0, v0
	v_add_f32_e32 v2, v14, v2
	v_add_f32_e32 v14, v104, v95
	v_add_f32_e32 v14, v14, v2
	v_mov_b32_e32 v15, v14
	v_cvt_pk_bf16_f32 v80, v3, v5
	v_cvt_pk_bf16_f32 v81, v7, v9
	v_cvt_pk_bf16_f32 v82, v10, v11
	v_cvt_pk_bf16_f32 v83, v12, v13
	v_cvt_pk_bf16_f32 v10, v97, v98
	v_cvt_pk_bf16_f32 v11, v99, v100
	v_cvt_pk_bf16_f32 v12, v101, v102
	v_cvt_pk_bf16_f32 v13, v103, v104
	v_cvt_pk_bf16_f32 v6, v4, v6
	v_cvt_pk_bf16_f32 v7, v8, v96
	v_cvt_pk_bf16_f32 v8, v84, v85
	v_cvt_pk_bf16_f32 v9, v86, v87
	v_cvt_pk_bf16_f32 v2, v88, v89
	v_cvt_pk_bf16_f32 v3, v90, v91
	v_cvt_pk_bf16_f32 v4, v92, v93
	v_cvt_pk_bf16_f32 v5, v94, v95
	s_nop 1
	v_permlane32_swap_b32_e32 v14, v15
	v_permlane32_swap_b32_e32 v80, v82
	v_permlane32_swap_b32_e32 v81, v83
	v_permlane32_swap_b32_e32 v10, v12
	v_permlane32_swap_b32_e32 v11, v13
	v_permlane32_swap_b32_e32 v6, v8
	v_permlane32_swap_b32_e32 v7, v9
	v_permlane32_swap_b32_e32 v2, v4
	v_permlane32_swap_b32_e32 v3, v5
	s_cbranch_vccnz .LBB0_1189
	s_and_saveexec_b64 s[6:7], s[0:1]
	ds_write_b32 v154, v0 offset:128
	s_or_b64 exec, exec, s[6:7]
	s_waitcnt lgkmcnt(0)
	v_add_u32_e32 v96, v151, v153
	ds_read_b128 v[84:87], v96 offset:224
	ds_read_b128 v[88:91], v96 offset:192
	ds_read_b128 v[92:95], v96 offset:160
	ds_read_b128 v[96:99], v96 offset:128
	s_waitcnt lgkmcnt(3)
	v_pk_mul_f32 v[76:77], v[76:77], v[84:85]
	s_waitcnt lgkmcnt(2)
	v_pk_mul_f32 v[72:73], v[72:73], v[88:89]
	s_waitcnt lgkmcnt(1)
	v_pk_mul_f32 v[68:69], v[68:69], v[92:93]
	v_pk_mul_f32 v[78:79], v[78:79], v[86:87]
	v_pk_mul_f32 v[74:75], v[74:75], v[90:91]
	v_pk_mul_f32 v[70:71], v[70:71], v[94:95]
	s_waitcnt lgkmcnt(0)
	v_pk_mul_f32 v[66:67], v[66:67], v[98:99]
	v_pk_mul_f32 v[64:65], v[64:65], v[96:97]
	v_pk_mul_f32 v[60:61], v[60:61], v[84:85]
	v_pk_mul_f32 v[56:57], v[56:57], v[88:89]
	v_pk_mul_f32 v[52:53], v[52:53], v[92:93]
	v_pk_mul_f32 v[62:63], v[62:63], v[86:87]
	v_pk_mul_f32 v[58:59], v[58:59], v[90:91]
	v_pk_mul_f32 v[54:55], v[54:55], v[94:95]
	v_pk_mul_f32 v[50:51], v[50:51], v[98:99]
	v_pk_mul_f32 v[48:49], v[48:49], v[96:97]
	v_pk_mul_f32 v[44:45], v[44:45], v[84:85]
	v_pk_mul_f32 v[40:41], v[40:41], v[88:89]
	v_pk_mul_f32 v[36:37], v[36:37], v[92:93]
	v_pk_mul_f32 v[46:47], v[46:47], v[86:87]
	v_pk_mul_f32 v[42:43], v[42:43], v[90:91]
	v_pk_mul_f32 v[38:39], v[38:39], v[94:95]
	v_pk_mul_f32 v[34:35], v[34:35], v[98:99]
	v_pk_mul_f32 v[32:33], v[32:33], v[96:97]
	v_pk_mul_f32 v[28:29], v[28:29], v[84:85]
	v_pk_mul_f32 v[24:25], v[24:25], v[88:89]
	v_pk_mul_f32 v[20:21], v[20:21], v[92:93]
	v_pk_mul_f32 v[30:31], v[30:31], v[86:87]
	v_pk_mul_f32 v[26:27], v[26:27], v[90:91]
	v_pk_mul_f32 v[22:23], v[22:23], v[94:95]
	v_pk_mul_f32 v[18:19], v[18:19], v[98:99]
	v_pk_mul_f32 v[16:17], v[16:17], v[96:97]

.LBB0_1262:
	v_max_f32_e32 v0, v66, v67
	v_max3_f32 v0, v0, v68, v69
	v_max3_f32 v0, v0, v70, v71
	v_max3_f32 v0, v0, v72, v73
	v_max3_f32 v0, v0, v74, v75
	v_max3_f32 v0, v0, v76, v77
	v_max3_f32 v0, v0, v78, v79
	v_max3_f32 v0, v0, v80, v81
	v_max3_f32 v0, v0, v82, v83
	v_max3_f32 v0, v0, v84, v85
	v_max3_f32 v0, v0, v86, v87
	v_max3_f32 v0, v0, v88, v89
	v_max3_f32 v0, v0, v90, v91
	v_max3_f32 v0, v0, v92, v93
	v_max3_f32 v0, v0, v94, v95
	v_max3_f32 v0, v0, v96, v97
	v_mov_b32_e32 v130, v0
	s_nop 1
	v_permlane32_swap_b32_e32 v0, v130
	v_max_f32_e32 v0, v0, v130
	v_sub_f32_e32 v130, v0, v186
	v_cmp_ge_f32_e32 vcc, s86, v130
	s_cmp_eq_u64 vcc, exec
	v_max_f32_e32 v130, v186, v0
	s_cselect_b64 vcc, -1, 0
	v_cndmask_b32_e32 v192, v130, v186, vcc
	v_sub_f32_e32 v66, v66, v192
	v_sub_f32_e32 v82, v82, v192
	v_exp_f32_e32 v66, v66
	v_exp_f32_e32 v82, v82
	v_sub_f32_e32 v67, v67, v192
	v_sub_f32_e32 v83, v83, v192
	v_exp_f32_e32 v67, v67
	v_exp_f32_e32 v83, v83
	v_sub_f32_e32 v68, v68, v192
	v_sub_f32_e32 v84, v84, v192
	v_exp_f32_e32 v68, v68
	v_exp_f32_e32 v84, v84
	v_sub_f32_e32 v69, v69, v192
	v_sub_f32_e32 v85, v85, v192
	v_exp_f32_e32 v69, v69
	v_exp_f32_e32 v85, v85
	v_sub_f32_e32 v70, v70, v192
	v_sub_f32_e32 v86, v86, v192
	v_sub_f32_e32 v0, v186, v130
	v_exp_f32_e32 v70, v70
	v_exp_f32_e32 v86, v86
	v_sub_f32_e32 v71, v71, v192
	v_sub_f32_e32 v87, v87, v192
	v_add_f32_e32 v130, v66, v82
	v_exp_f32_e32 v71, v71
	v_exp_f32_e32 v87, v87
	v_sub_f32_e32 v72, v72, v192
	v_sub_f32_e32 v88, v88, v192
	v_add_f32_e32 v130, 0, v130
	v_add_f32_e32 v131, v67, v83
	v_exp_f32_e32 v72, v72
	v_exp_f32_e32 v88, v88
	v_sub_f32_e32 v73, v73, v192
	v_sub_f32_e32 v89, v89, v192
	v_add_f32_e32 v130, v131, v130
	v_add_f32_e32 v131, v68, v84
	v_exp_f32_e32 v73, v73
	v_exp_f32_e32 v89, v89
	v_sub_f32_e32 v74, v74, v192
	v_sub_f32_e32 v90, v90, v192
	v_add_f32_e32 v130, v131, v130
	v_add_f32_e32 v131, v69, v85
	v_exp_f32_e32 v74, v74
	v_exp_f32_e32 v90, v90
	v_sub_f32_e32 v75, v75, v192
	v_sub_f32_e32 v91, v91, v192
	v_add_f32_e32 v130, v131, v130
	v_add_f32_e32 v131, v70, v86
	v_exp_f32_e32 v75, v75
	v_exp_f32_e32 v91, v91
	v_sub_f32_e32 v76, v76, v192
	v_sub_f32_e32 v92, v92, v192
	v_add_f32_e32 v130, v131, v130
	v_add_f32_e32 v131, v71, v87
	v_exp_f32_e32 v76, v76
	v_exp_f32_e32 v92, v92
	v_sub_f32_e32 v77, v77, v192
	v_sub_f32_e32 v93, v93, v192
	v_add_f32_e32 v130, v131, v130
	v_add_f32_e32 v131, v72, v88
	v_exp_f32_e32 v77, v77
	v_exp_f32_e32 v93, v93
	v_sub_f32_e32 v78, v78, v192
	v_sub_f32_e32 v94, v94, v192
	v_add_f32_e32 v130, v131, v130
	v_add_f32_e32 v131, v73, v89
	v_exp_f32_e32 v78, v78
	v_exp_f32_e32 v94, v94
	v_sub_f32_e32 v79, v79, v192
	v_sub_f32_e32 v95, v95, v192
	v_add_f32_e32 v130, v131, v130
	v_add_f32_e32 v131, v74, v90
	v_exp_f32_e32 v79, v79
	v_exp_f32_e32 v95, v95
	v_sub_f32_e32 v80, v80, v192
	v_sub_f32_e32 v96, v96, v192
	v_add_f32_e32 v130, v131, v130
	v_add_f32_e32 v131, v75, v91
	v_exp_f32_e32 v80, v80
	v_exp_f32_e32 v96, v96
	v_sub_f32_e32 v81, v81, v192
	v_sub_f32_e32 v97, v97, v192
	v_add_f32_e32 v130, v131, v130
	v_add_f32_e32 v131, v76, v92
	v_exp_f32_e32 v81, v81
	v_exp_f32_e32 v97, v97
	v_add_f32_e32 v130, v131, v130
	v_add_f32_e32 v131, v77, v93
	v_add_f32_e32 v130, v131, v130
	v_add_f32_e32 v131, v78, v94
	v_add_f32_e32 v130, v131, v130
	v_add_f32_e32 v131, v79, v95
	v_add_f32_e32 v130, v131, v130
	v_add_f32_e32 v131, v80, v96
	v_exp_f32_e32 v0, v0
	v_add_f32_e32 v130, v131, v130
	v_add_f32_e32 v131, v81, v97
	v_add_f32_e32 v186, v131, v130
	v_mov_b32_e32 v193, v186
	v_cvt_pk_bf16_f32 v142, v66, v67
	v_cvt_pk_bf16_f32 v143, v68, v69
	v_cvt_pk_bf16_f32 v144, v70, v71
	v_cvt_pk_bf16_f32 v145, v72, v73
	v_cvt_pk_bf16_f32 v138, v74, v75
	v_cvt_pk_bf16_f32 v139, v76, v77
	v_cvt_pk_bf16_f32 v140, v78, v79
	v_cvt_pk_bf16_f32 v141, v80, v81
	v_cvt_pk_bf16_f32 v134, v82, v83
	v_cvt_pk_bf16_f32 v135, v84, v85
	v_cvt_pk_bf16_f32 v136, v86, v87
	v_cvt_pk_bf16_f32 v137, v88, v89
	v_cvt_pk_bf16_f32 v130, v90, v91
	v_cvt_pk_bf16_f32 v131, v92, v93
	v_cvt_pk_bf16_f32 v132, v94, v95
	v_cvt_pk_bf16_f32 v133, v96, v97
	s_nop 1
	v_permlane32_swap_b32_e32 v186, v193
	v_permlane32_swap_b32_e32 v142, v144
	v_permlane32_swap_b32_e32 v143, v145
	v_permlane32_swap_b32_e32 v138, v140
	v_permlane32_swap_b32_e32 v139, v141
	v_permlane32_swap_b32_e32 v134, v136
	v_permlane32_swap_b32_e32 v135, v137
	v_permlane32_swap_b32_e32 v130, v132
	v_permlane32_swap_b32_e32 v131, v133
	s_cbranch_vccnz .LBB0_1266
	s_and_saveexec_b64 s[8:9], s[0:1]
	ds_write_b32 v221, v0 offset:128
	s_or_b64 exec, exec, s[8:9]
	s_waitcnt lgkmcnt(0)
	v_add_u32_e32 v201, v189, v199
	ds_read_b128 v[206:209], v201 offset:224
	ds_read_b128 v[224:227], v201 offset:192
	ds_read_b128 v[228:231], v201 offset:160
	ds_read_b128 v[232:235], v201 offset:128
	s_waitcnt lgkmcnt(0)
	v_pk_mul_f32 v[62:63], v[62:63], v[206:207]
	v_pk_mul_f32 v[58:59], v[58:59], v[224:225]
	v_pk_mul_f32 v[54:55], v[54:55], v[228:229]
	v_pk_mul_f32 v[64:65], v[64:65], v[208:209]
	v_pk_mul_f32 v[60:61], v[60:61], v[226:227]
	v_pk_mul_f32 v[56:57], v[56:57], v[230:231]
	v_pk_mul_f32 v[52:53], v[52:53], v[234:235]
	v_pk_mul_f32 v[50:51], v[50:51], v[232:233]
	v_pk_mul_f32 v[46:47], v[46:47], v[206:207]
	v_pk_mul_f32 v[42:43], v[42:43], v[224:225]
	v_pk_mul_f32 v[38:39], v[38:39], v[228:229]
	v_pk_mul_f32 v[48:49], v[48:49], v[208:209]
	v_pk_mul_f32 v[44:45], v[44:45], v[226:227]
	v_pk_mul_f32 v[40:41], v[40:41], v[230:231]
	v_pk_mul_f32 v[36:37], v[36:37], v[234:235]
	v_pk_mul_f32 v[34:35], v[34:35], v[232:233]
	v_pk_mul_f32 v[30:31], v[30:31], v[206:207]
	v_pk_mul_f32 v[26:27], v[26:27], v[224:225]
	v_pk_mul_f32 v[22:23], v[22:23], v[228:229]
	v_pk_mul_f32 v[32:33], v[32:33], v[208:209]
	v_pk_mul_f32 v[28:29], v[28:29], v[226:227]
	v_pk_mul_f32 v[24:25], v[24:25], v[230:231]
	v_pk_mul_f32 v[20:21], v[20:21], v[234:235]
	v_pk_mul_f32 v[18:19], v[18:19], v[232:233]
	v_pk_mul_f32 v[14:15], v[14:15], v[206:207]
	v_pk_mul_f32 v[10:11], v[10:11], v[224:225]
	v_pk_mul_f32 v[6:7], v[6:7], v[228:229]
	v_pk_mul_f32 v[16:17], v[16:17], v[208:209]
	v_pk_mul_f32 v[12:13], v[12:13], v[226:227]
	v_pk_mul_f32 v[8:9], v[8:9], v[230:231]
	v_pk_mul_f32 v[4:5], v[4:5], v[234:235]
	v_pk_mul_f32 v[2:3], v[2:3], v[232:233]

.LBB0_1268:
	s_nop 0
	v_max_f32_e32 v0, v66, v67
	v_max3_f32 v0, v0, v68, v69
	v_max3_f32 v0, v0, v70, v71
	v_max3_f32 v0, v0, v72, v73
	v_max3_f32 v0, v0, v74, v75
	v_max3_f32 v0, v0, v76, v77
	v_max3_f32 v0, v0, v78, v79
	v_max3_f32 v0, v0, v80, v81
	v_max3_f32 v0, v0, v82, v83
	v_max3_f32 v0, v0, v84, v85
	v_max3_f32 v0, v0, v86, v87
	v_max3_f32 v0, v0, v88, v89
	v_max3_f32 v0, v0, v90, v91
	v_max3_f32 v0, v0, v92, v93
	v_max3_f32 v0, v0, v94, v95
	v_max3_f32 v0, v0, v96, v97
	v_mov_b32_e32 v130, v0
	s_nop 1
	v_permlane32_swap_b32_e32 v0, v130
	v_max_f32_e32 v0, v0, v130
	v_sub_f32_e32 v130, v0, v186
	v_cmp_ge_f32_e32 vcc, s86, v130
	s_cmp_eq_u64 vcc, exec
	v_max_f32_e32 v130, v186, v0
	s_cselect_b64 vcc, -1, 0
	v_cndmask_b32_e32 v192, v130, v186, vcc
	v_sub_f32_e32 v66, v66, v192
	v_sub_f32_e32 v82, v82, v192
	v_exp_f32_e32 v66, v66
	v_exp_f32_e32 v82, v82
	v_sub_f32_e32 v67, v67, v192
	v_sub_f32_e32 v83, v83, v192
	v_exp_f32_e32 v67, v67
	v_exp_f32_e32 v83, v83
	v_sub_f32_e32 v68, v68, v192
	v_sub_f32_e32 v84, v84, v192
	v_exp_f32_e32 v68, v68
	v_exp_f32_e32 v84, v84
	v_sub_f32_e32 v69, v69, v192
	v_sub_f32_e32 v85, v85, v192
	v_exp_f32_e32 v69, v69
	v_exp_f32_e32 v85, v85
	v_sub_f32_e32 v70, v70, v192
	v_sub_f32_e32 v86, v86, v192
	v_sub_f32_e32 v0, v186, v130
	v_exp_f32_e32 v70, v70
	v_exp_f32_e32 v86, v86
	v_sub_f32_e32 v71, v71, v192
	v_sub_f32_e32 v87, v87, v192
	v_add_f32_e32 v130, v66, v82
	v_exp_f32_e32 v71, v71
	v_exp_f32_e32 v87, v87
	v_sub_f32_e32 v72, v72, v192
	v_sub_f32_e32 v88, v88, v192
	v_add_f32_e32 v130, 0, v130
	v_add_f32_e32 v131, v67, v83
	v_exp_f32_e32 v72, v72
	v_exp_f32_e32 v88, v88
	v_sub_f32_e32 v73, v73, v192
	v_sub_f32_e32 v89, v89, v192
	v_add_f32_e32 v130, v131, v130
	v_add_f32_e32 v131, v68, v84
	v_exp_f32_e32 v73, v73
	v_exp_f32_e32 v89, v89
	v_sub_f32_e32 v74, v74, v192
	v_sub_f32_e32 v90, v90, v192
	v_add_f32_e32 v130, v131, v130
	v_add_f32_e32 v131, v69, v85
	v_exp_f32_e32 v74, v74
	v_exp_f32_e32 v90, v90
	v_sub_f32_e32 v75, v75, v192
	v_sub_f32_e32 v91, v91, v192
	v_add_f32_e32 v130, v131, v130
	v_add_f32_e32 v131, v70, v86
	v_exp_f32_e32 v75, v75
	v_exp_f32_e32 v91, v91
	v_sub_f32_e32 v76, v76, v192
	v_sub_f32_e32 v92, v92, v192
	v_add_f32_e32 v130, v131, v130
	v_add_f32_e32 v131, v71, v87
	v_exp_f32_e32 v76, v76
	v_exp_f32_e32 v92, v92
	v_sub_f32_e32 v77, v77, v192
	v_sub_f32_e32 v93, v93, v192
	v_add_f32_e32 v130, v131, v130
	v_add_f32_e32 v131, v72, v88
	v_exp_f32_e32 v77, v77
	v_exp_f32_e32 v93, v93
	v_sub_f32_e32 v78, v78, v192
	v_sub_f32_e32 v94, v94, v192
	v_add_f32_e32 v130, v131, v130
	v_add_f32_e32 v131, v73, v89
	v_exp_f32_e32 v78, v78
	v_exp_f32_e32 v94, v94
	v_sub_f32_e32 v79, v79, v192
	v_sub_f32_e32 v95, v95, v192
	v_add_f32_e32 v130, v131, v130
	v_add_f32_e32 v131, v74, v90
	v_exp_f32_e32 v79, v79
	v_exp_f32_e32 v95, v95
	v_sub_f32_e32 v80, v80, v192
	v_sub_f32_e32 v96, v96, v192
	v_add_f32_e32 v130, v131, v130
	v_add_f32_e32 v131, v75, v91
	v_exp_f32_e32 v80, v80
	v_exp_f32_e32 v96, v96
	v_sub_f32_e32 v81, v81, v192
	v_sub_f32_e32 v97, v97, v192
	v_add_f32_e32 v130, v131, v130
	v_add_f32_e32 v131, v76, v92
	v_exp_f32_e32 v81, v81
	v_exp_f32_e32 v97, v97
	v_add_f32_e32 v130, v131, v130
	v_add_f32_e32 v131, v77, v93
	v_add_f32_e32 v130, v131, v130
	v_add_f32_e32 v131, v78, v94
	v_add_f32_e32 v130, v131, v130
	v_add_f32_e32 v131, v79, v95
	v_add_f32_e32 v130, v131, v130
	v_add_f32_e32 v131, v80, v96
	v_exp_f32_e32 v0, v0
	v_add_f32_e32 v130, v131, v130
	v_add_f32_e32 v131, v81, v97
	v_add_f32_e32 v186, v131, v130
	v_mov_b32_e32 v193, v186
	v_cvt_pk_bf16_f32 v142, v66, v67
	v_cvt_pk_bf16_f32 v143, v68, v69
	v_cvt_pk_bf16_f32 v144, v70, v71
	v_cvt_pk_bf16_f32 v145, v72, v73
	v_cvt_pk_bf16_f32 v138, v74, v75
	v_cvt_pk_bf16_f32 v139, v76, v77
	v_cvt_pk_bf16_f32 v140, v78, v79
	v_cvt_pk_bf16_f32 v141, v80, v81
	v_cvt_pk_bf16_f32 v134, v82, v83
	v_cvt_pk_bf16_f32 v135, v84, v85
	v_cvt_pk_bf16_f32 v136, v86, v87
	v_cvt_pk_bf16_f32 v137, v88, v89
	v_cvt_pk_bf16_f32 v130, v90, v91
	v_cvt_pk_bf16_f32 v131, v92, v93
	v_cvt_pk_bf16_f32 v132, v94, v95
	v_cvt_pk_bf16_f32 v133, v96, v97
	s_nop 1
	v_permlane32_swap_b32_e32 v186, v193
	v_permlane32_swap_b32_e32 v142, v144
	v_permlane32_swap_b32_e32 v143, v145
	v_permlane32_swap_b32_e32 v138, v140
	v_permlane32_swap_b32_e32 v139, v141
	v_permlane32_swap_b32_e32 v134, v136
	v_permlane32_swap_b32_e32 v135, v137
	v_permlane32_swap_b32_e32 v130, v132
	v_permlane32_swap_b32_e32 v131, v133
	s_cbranch_vccnz .LBB0_1272
	s_and_saveexec_b64 s[26:27], s[0:1]
	ds_write_b32 v221, v0 offset:128
	s_or_b64 exec, exec, s[26:27]
	s_waitcnt lgkmcnt(0)
	v_add_u32_e32 v201, v189, v199
	ds_read_b128 v[206:209], v201 offset:224
	ds_read_b128 v[210:213], v201 offset:192
	ds_read_b128 v[224:227], v201 offset:160
	ds_read_b128 v[228:231], v201 offset:128
	s_waitcnt lgkmcnt(0)
	v_pk_mul_f32 v[62:63], v[62:63], v[206:207]
	v_pk_mul_f32 v[58:59], v[58:59], v[210:211]
	v_pk_mul_f32 v[54:55], v[54:55], v[224:225]
	v_pk_mul_f32 v[64:65], v[64:65], v[208:209]
	v_pk_mul_f32 v[60:61], v[60:61], v[212:213]
	v_pk_mul_f32 v[56:57], v[56:57], v[226:227]
	v_pk_mul_f32 v[52:53], v[52:53], v[230:231]
	v_pk_mul_f32 v[50:51], v[50:51], v[228:229]
	v_pk_mul_f32 v[46:47], v[46:47], v[206:207]
	v_pk_mul_f32 v[42:43], v[42:43], v[210:211]
	v_pk_mul_f32 v[38:39], v[38:39], v[224:225]
	v_pk_mul_f32 v[48:49], v[48:49], v[208:209]
	v_pk_mul_f32 v[44:45], v[44:45], v[212:213]
	v_pk_mul_f32 v[40:41], v[40:41], v[226:227]
	v_pk_mul_f32 v[36:37], v[36:37], v[230:231]
	v_pk_mul_f32 v[34:35], v[34:35], v[228:229]
	v_pk_mul_f32 v[30:31], v[30:31], v[206:207]
	v_pk_mul_f32 v[26:27], v[26:27], v[210:211]
	v_pk_mul_f32 v[22:23], v[22:23], v[224:225]
	v_pk_mul_f32 v[32:33], v[32:33], v[208:209]
	v_pk_mul_f32 v[28:29], v[28:29], v[212:213]
	v_pk_mul_f32 v[24:25], v[24:25], v[226:227]
	v_pk_mul_f32 v[20:21], v[20:21], v[230:231]
	v_pk_mul_f32 v[18:19], v[18:19], v[228:229]
	v_pk_mul_f32 v[14:15], v[14:15], v[206:207]
	v_pk_mul_f32 v[10:11], v[10:11], v[210:211]
	v_pk_mul_f32 v[6:7], v[6:7], v[224:225]
	v_pk_mul_f32 v[16:17], v[16:17], v[208:209]
	v_pk_mul_f32 v[12:13], v[12:13], v[212:213]
	v_pk_mul_f32 v[8:9], v[8:9], v[226:227]
	v_pk_mul_f32 v[4:5], v[4:5], v[230:231]
	v_pk_mul_f32 v[2:3], v[2:3], v[228:229]
